# K-loops: priority lowered before the LAST MFMA of a block (instead of after the closing barrier), on top of v21
# baseline (speedup 1.0000x reference)
.LBB0_446:
	ds_read_b128 v[148:151], v165
	ds_read_b128 v[174:177], v165 offset:1024
	ds_read_b128 v[180:183], v165 offset:2048
	ds_read_b128 v[184:187], v165 offset:3072
	ds_read_b128 v[188:191], v169
	ds_read_b128 v[192:195], v169 offset:1024
	ds_read_b128 v[196:199], v169 offset:2048
	ds_read_b128 v[200:203], v169 offset:3072
	s_add_u32 s50, s4, 0xfff00080
	s_addc_u32 s51, s5, -1
	s_cmp_eq_u32 s68, 60
	s_cselect_b32 s53, s3, s51
	s_cselect_b32 s52, s8, s50
	s_cselect_b32 s51, s39, s65
	s_cselect_b32 s50, s45, s63
	v_lshl_add_u64 v[154:155], s[4:5], 0, v[140:141]
	s_add_i32 m0, s7, 0xc000
	ds_read_b128 v[204:207], v173
	ds_read_b128 v[208:211], v173 offset:1024
	ds_read_b128 v[212:215], v173 offset:2048
	ds_read_b128 v[216:219], v173 offset:3072
	ds_read_b128 v[220:223], v173 offset:4096
	ds_read_b128 v[224:227], v173 offset:5120
	ds_read_b128 v[228:231], v173 offset:6144
	ds_read_b128 v[236:239], v173 offset:7168
	global_load_lds_dwordx4 v[154:155], off
	v_lshl_add_u64 v[154:155], s[4:5], 0, v[142:143]
	s_add_i32 m0, s7, 0xe000
	s_nop 0
	global_load_lds_dwordx4 v[154:155], off
	s_setprio 1
	s_waitcnt vmcnt(8) lgkmcnt(0)
	s_barrier
	v_mfma_f32_16x16x32_bf16 v[126:129], v[148:151], v[204:207], v[126:129]
	v_mfma_f32_16x16x32_bf16 v[122:125], v[180:183], v[204:207], v[122:125]
	v_mfma_f32_16x16x32_bf16 v[110:113], v[148:151], v[212:215], v[110:113]
	v_mfma_f32_16x16x32_bf16 v[106:109], v[180:183], v[212:215], v[106:109]
	v_mfma_f32_16x16x32_bf16 v[94:97], v[148:151], v[220:223], v[94:97]
	v_mfma_f32_16x16x32_bf16 v[90:93], v[180:183], v[220:223], v[90:93]
	v_mfma_f32_16x16x32_bf16 v[78:81], v[148:151], v[228:231], v[78:81]
	v_mfma_f32_16x16x32_bf16 v[74:77], v[180:183], v[228:231], v[74:77]
	v_mfma_f32_16x16x32_bf16 v[126:129], v[174:177], v[208:211], v[126:129]
	v_mfma_f32_16x16x32_bf16 v[122:125], v[184:187], v[208:211], v[122:125]
	v_mfma_f32_16x16x32_bf16 v[110:113], v[174:177], v[216:219], v[110:113]
	v_mfma_f32_16x16x32_bf16 v[106:109], v[184:187], v[216:219], v[106:109]
	v_mfma_f32_16x16x32_bf16 v[94:97], v[174:177], v[224:227], v[94:97]
	v_mfma_f32_16x16x32_bf16 v[90:93], v[184:187], v[224:227], v[90:93]
	v_mfma_f32_16x16x32_bf16 v[78:81], v[174:177], v[236:239], v[78:81]
	v_mfma_f32_16x16x32_bf16 v[74:77], v[184:187], v[236:239], v[74:77]
	v_mfma_f32_16x16x32_bf16 v[118:121], v[188:191], v[204:207], v[118:121]
	v_mfma_f32_16x16x32_bf16 v[114:117], v[196:199], v[204:207], v[114:117]
	v_mfma_f32_16x16x32_bf16 v[102:105], v[188:191], v[212:215], v[102:105]
	v_mfma_f32_16x16x32_bf16 v[98:101], v[196:199], v[212:215], v[98:101]
	v_mfma_f32_16x16x32_bf16 v[86:89], v[188:191], v[220:223], v[86:89]
	v_mfma_f32_16x16x32_bf16 v[82:85], v[196:199], v[220:223], v[82:85]
	v_mfma_f32_16x16x32_bf16 v[70:73], v[188:191], v[228:231], v[70:73]
	v_mfma_f32_16x16x32_bf16 v[66:69], v[196:199], v[228:231], v[66:69]
	v_mfma_f32_16x16x32_bf16 v[118:121], v[192:195], v[208:211], v[118:121]
	v_mfma_f32_16x16x32_bf16 v[114:117], v[200:203], v[208:211], v[114:117]
	v_mfma_f32_16x16x32_bf16 v[102:105], v[192:195], v[216:219], v[102:105]
	v_mfma_f32_16x16x32_bf16 v[98:101], v[200:203], v[216:219], v[98:101]
	v_mfma_f32_16x16x32_bf16 v[86:89], v[192:195], v[224:227], v[86:89]
	v_mfma_f32_16x16x32_bf16 v[82:85], v[200:203], v[224:227], v[82:85]
	v_mfma_f32_16x16x32_bf16 v[70:73], v[192:195], v[236:239], v[70:73]
	s_setprio 0
	v_mfma_f32_16x16x32_bf16 v[66:69], v[200:203], v[236:239], v[66:69]
	s_barrier
	s_add_i32 s69, s59, s35
	v_lshl_add_u64 v[154:155], s[50:51], 0, v[132:133]
	s_mov_b32 m0, s69
	ds_read_b128 v[204:207], v173 offset:16384
	ds_read_b128 v[208:211], v173 offset:17408
	ds_read_b128 v[212:215], v173 offset:18432
	ds_read_b128 v[216:219], v173 offset:19456
	ds_read_b128 v[220:223], v173 offset:20480
	ds_read_b128 v[224:227], v173 offset:21504
	ds_read_b128 v[228:231], v173 offset:22528
	ds_read_b128 v[236:239], v173 offset:23552
	global_load_lds_dwordx4 v[154:155], off
	s_add_i32 m0, s69, 0x2000
	s_add_u32 s70, s50, 0x100000
	v_lshl_add_u64 v[158:159], s[50:51], 0, v[136:137]
	s_addc_u32 s71, s51, 0
	s_add_i32 s69, s60, s35
	global_load_lds_dwordx4 v[158:159], off
	v_lshl_add_u64 v[162:163], s[70:71], 0, v[132:133]
	s_mov_b32 m0, s69
	v_lshl_add_u64 v[166:167], s[52:53], 0, v[134:135]
	global_load_lds_dwordx4 v[162:163], off
	v_lshl_add_u64 v[162:163], s[70:71], 0, v[136:137]
	s_add_i32 m0, s69, 0x2000
	s_nop 0
	global_load_lds_dwordx4 v[162:163], off
	v_lshl_add_u64 v[162:163], s[52:53], 0, v[130:131]
	s_mov_b32 m0, s7
	s_nop 0
	global_load_lds_dwordx4 v[162:163], off
	s_mov_b32 m0, s37
	s_nop 0
	global_load_lds_dwordx4 v[166:167], off
	s_setprio 1
	s_waitcnt vmcnt(8) lgkmcnt(0)
	s_barrier
	v_mfma_f32_16x16x32_bf16 v[62:65], v[148:151], v[204:207], v[62:65]
	v_mfma_f32_16x16x32_bf16 v[58:61], v[180:183], v[204:207], v[58:61]
	v_mfma_f32_16x16x32_bf16 v[46:49], v[148:151], v[212:215], v[46:49]
	v_mfma_f32_16x16x32_bf16 v[42:45], v[180:183], v[212:215], v[42:45]
	v_mfma_f32_16x16x32_bf16 v[30:33], v[148:151], v[220:223], v[30:33]
	v_mfma_f32_16x16x32_bf16 v[26:29], v[180:183], v[220:223], v[26:29]
	v_mfma_f32_16x16x32_bf16 v[14:17], v[148:151], v[228:231], v[14:17]
	v_mfma_f32_16x16x32_bf16 v[10:13], v[180:183], v[228:231], v[10:13]
	v_mfma_f32_16x16x32_bf16 v[62:65], v[174:177], v[208:211], v[62:65]
	v_mfma_f32_16x16x32_bf16 v[58:61], v[184:187], v[208:211], v[58:61]
	v_mfma_f32_16x16x32_bf16 v[46:49], v[174:177], v[216:219], v[46:49]
	v_mfma_f32_16x16x32_bf16 v[42:45], v[184:187], v[216:219], v[42:45]
	v_mfma_f32_16x16x32_bf16 v[30:33], v[174:177], v[224:227], v[30:33]
	v_mfma_f32_16x16x32_bf16 v[26:29], v[184:187], v[224:227], v[26:29]
	v_mfma_f32_16x16x32_bf16 v[14:17], v[174:177], v[236:239], v[14:17]
	v_mfma_f32_16x16x32_bf16 v[10:13], v[184:187], v[236:239], v[10:13]
	v_mfma_f32_16x16x32_bf16 v[54:57], v[188:191], v[204:207], v[54:57]
	v_mfma_f32_16x16x32_bf16 v[50:53], v[196:199], v[204:207], v[50:53]
	v_mfma_f32_16x16x32_bf16 v[38:41], v[188:191], v[212:215], v[38:41]
	v_mfma_f32_16x16x32_bf16 v[34:37], v[196:199], v[212:215], v[34:37]
	v_mfma_f32_16x16x32_bf16 v[22:25], v[188:191], v[220:223], v[22:25]
	v_mfma_f32_16x16x32_bf16 v[18:21], v[196:199], v[220:223], v[18:21]
	v_mfma_f32_16x16x32_bf16 v[6:9], v[188:191], v[228:231], v[6:9]
	v_mfma_f32_16x16x32_bf16 v[2:5], v[196:199], v[228:231], v[2:5]
	v_mfma_f32_16x16x32_bf16 v[54:57], v[192:195], v[208:211], v[54:57]
	v_mfma_f32_16x16x32_bf16 v[50:53], v[200:203], v[208:211], v[50:53]
	v_mfma_f32_16x16x32_bf16 v[38:41], v[192:195], v[216:219], v[38:41]
	v_mfma_f32_16x16x32_bf16 v[34:37], v[200:203], v[216:219], v[34:37]
	v_mfma_f32_16x16x32_bf16 v[22:25], v[192:195], v[224:227], v[22:25]
	v_mfma_f32_16x16x32_bf16 v[18:21], v[200:203], v[224:227], v[18:21]
	v_mfma_f32_16x16x32_bf16 v[6:9], v[192:195], v[236:239], v[6:9]
	s_setprio 0
	v_mfma_f32_16x16x32_bf16 v[2:5], v[200:203], v[236:239], v[2:5]
	s_barrier
	s_add_i32 s69, 0, 0x18000
	v_add_u32_e32 v139, s69, v161
	s_add_i32 s70, 0, 0x1c000
	ds_read_b128 v[148:151], v139
	ds_read_b128 v[174:177], v139 offset:1024
	ds_read_b128 v[180:183], v139 offset:2048
	ds_read_b128 v[184:187], v139 offset:3072
	v_add_u32_e32 v139, s70, v161
	ds_read_b128 v[188:191], v139
	ds_read_b128 v[192:195], v139 offset:1024
	ds_read_b128 v[196:199], v139 offset:2048
	ds_read_b128 v[200:203], v139 offset:3072
	s_add_u32 s52, s52, 0x100000
	s_addc_u32 s53, s53, 0
	s_mov_b32 m0, s41
	v_lshl_add_u64 v[170:171], s[52:53], 0, v[130:131]
	ds_read_b128 v[204:207], v173 offset:32768
	ds_read_b128 v[208:211], v173 offset:33792
	ds_read_b128 v[212:215], v173 offset:34816
	ds_read_b128 v[216:219], v173 offset:35840
	ds_read_b128 v[220:223], v173 offset:36864
	ds_read_b128 v[224:227], v173 offset:37888
	ds_read_b128 v[228:231], v173 offset:38912
	ds_read_b128 v[236:239], v173 offset:39936
	global_load_lds_dwordx4 v[170:171], off
	v_lshl_add_u64 v[170:171], s[52:53], 0, v[134:135]
	s_mov_b32 m0, s43
	s_nop 0
	global_load_lds_dwordx4 v[170:171], off
	s_setprio 1
	s_waitcnt vmcnt(8) lgkmcnt(0)
	s_barrier
	v_mfma_f32_16x16x32_bf16 v[126:129], v[148:151], v[204:207], v[126:129]
	v_mfma_f32_16x16x32_bf16 v[122:125], v[180:183], v[204:207], v[122:125]
	v_mfma_f32_16x16x32_bf16 v[110:113], v[148:151], v[212:215], v[110:113]
	v_mfma_f32_16x16x32_bf16 v[106:109], v[180:183], v[212:215], v[106:109]
	v_mfma_f32_16x16x32_bf16 v[94:97], v[148:151], v[220:223], v[94:97]
	v_mfma_f32_16x16x32_bf16 v[90:93], v[180:183], v[220:223], v[90:93]
	v_mfma_f32_16x16x32_bf16 v[78:81], v[148:151], v[228:231], v[78:81]
	v_mfma_f32_16x16x32_bf16 v[74:77], v[180:183], v[228:231], v[74:77]
	v_mfma_f32_16x16x32_bf16 v[126:129], v[174:177], v[208:211], v[126:129]
	v_mfma_f32_16x16x32_bf16 v[122:125], v[184:187], v[208:211], v[122:125]
	v_mfma_f32_16x16x32_bf16 v[110:113], v[174:177], v[216:219], v[110:113]
	v_mfma_f32_16x16x32_bf16 v[106:109], v[184:187], v[216:219], v[106:109]
	v_mfma_f32_16x16x32_bf16 v[94:97], v[174:177], v[224:227], v[94:97]
	v_mfma_f32_16x16x32_bf16 v[90:93], v[184:187], v[224:227], v[90:93]
	v_mfma_f32_16x16x32_bf16 v[78:81], v[174:177], v[236:239], v[78:81]
	v_mfma_f32_16x16x32_bf16 v[74:77], v[184:187], v[236:239], v[74:77]
	v_mfma_f32_16x16x32_bf16 v[118:121], v[188:191], v[204:207], v[118:121]
	v_mfma_f32_16x16x32_bf16 v[114:117], v[196:199], v[204:207], v[114:117]
	v_mfma_f32_16x16x32_bf16 v[102:105], v[188:191], v[212:215], v[102:105]
	v_mfma_f32_16x16x32_bf16 v[98:101], v[196:199], v[212:215], v[98:101]
	v_mfma_f32_16x16x32_bf16 v[86:89], v[188:191], v[220:223], v[86:89]
	v_mfma_f32_16x16x32_bf16 v[82:85], v[196:199], v[220:223], v[82:85]
	v_mfma_f32_16x16x32_bf16 v[70:73], v[188:191], v[228:231], v[70:73]
	v_mfma_f32_16x16x32_bf16 v[66:69], v[196:199], v[228:231], v[66:69]
	v_mfma_f32_16x16x32_bf16 v[118:121], v[192:195], v[208:211], v[118:121]
	v_mfma_f32_16x16x32_bf16 v[114:117], v[200:203], v[208:211], v[114:117]
	v_mfma_f32_16x16x32_bf16 v[102:105], v[192:195], v[216:219], v[102:105]
	v_mfma_f32_16x16x32_bf16 v[98:101], v[200:203], v[216:219], v[98:101]
	v_mfma_f32_16x16x32_bf16 v[86:89], v[192:195], v[224:227], v[86:89]
	v_mfma_f32_16x16x32_bf16 v[82:85], v[200:203], v[224:227], v[82:85]
	v_mfma_f32_16x16x32_bf16 v[70:73], v[192:195], v[236:239], v[70:73]
	s_setprio 0
	v_mfma_f32_16x16x32_bf16 v[66:69], v[200:203], v[236:239], v[66:69]
	s_barrier
	s_add_i32 s52, s69, s35
	v_lshl_add_u64 v[154:155], v[154:155], 0, s[16:17]
	s_mov_b32 m0, s52
	ds_read_b128 v[204:207], v173 offset:49152
	ds_read_b128 v[208:211], v173 offset:50176
	ds_read_b128 v[212:215], v173 offset:51200
	ds_read_b128 v[216:219], v173 offset:52224
	ds_read_b128 v[220:223], v173 offset:53248
	ds_read_b128 v[224:227], v173 offset:54272
	ds_read_b128 v[228:231], v173 offset:55296
	ds_read_b128 v[236:239], v173 offset:56320
	global_load_lds_dwordx4 v[154:155], off
	s_add_i32 m0, s52, 0x2000
	s_add_u32 s50, s50, 0x100080
	v_lshl_add_u64 v[154:155], v[158:159], 0, s[16:17]
	s_addc_u32 s51, s51, 0
	s_add_i32 s52, s70, s35
	global_load_lds_dwordx4 v[154:155], off
	v_lshl_add_u64 v[154:155], s[50:51], 0, v[132:133]
	s_mov_b32 m0, s52
	s_nop 0
	global_load_lds_dwordx4 v[154:155], off
	v_lshl_add_u64 v[154:155], s[50:51], 0, v[136:137]
	s_add_i32 m0, s52, 0x2000
	s_nop 0
	global_load_lds_dwordx4 v[154:155], off
	v_lshl_add_u64 v[154:155], v[162:163], 0, s[16:17]
	s_mov_b32 m0, s57
	s_nop 0
	global_load_lds_dwordx4 v[154:155], off
	v_lshl_add_u64 v[154:155], v[166:167], 0, s[16:17]
	s_mov_b32 m0, s58
	s_nop 0
	global_load_lds_dwordx4 v[154:155], off
	s_setprio 1
	s_waitcnt vmcnt(8) lgkmcnt(0)
	s_barrier
	v_mfma_f32_16x16x32_bf16 v[62:65], v[148:151], v[204:207], v[62:65]
	v_mfma_f32_16x16x32_bf16 v[58:61], v[180:183], v[204:207], v[58:61]
	v_mfma_f32_16x16x32_bf16 v[46:49], v[148:151], v[212:215], v[46:49]
	v_mfma_f32_16x16x32_bf16 v[42:45], v[180:183], v[212:215], v[42:45]
	v_mfma_f32_16x16x32_bf16 v[30:33], v[148:151], v[220:223], v[30:33]
	v_mfma_f32_16x16x32_bf16 v[26:29], v[180:183], v[220:223], v[26:29]
	v_mfma_f32_16x16x32_bf16 v[14:17], v[148:151], v[228:231], v[14:17]
	v_mfma_f32_16x16x32_bf16 v[10:13], v[180:183], v[228:231], v[10:13]
	v_mfma_f32_16x16x32_bf16 v[62:65], v[174:177], v[208:211], v[62:65]
	v_mfma_f32_16x16x32_bf16 v[58:61], v[184:187], v[208:211], v[58:61]
	v_mfma_f32_16x16x32_bf16 v[46:49], v[174:177], v[216:219], v[46:49]
	v_mfma_f32_16x16x32_bf16 v[42:45], v[184:187], v[216:219], v[42:45]
	v_mfma_f32_16x16x32_bf16 v[30:33], v[174:177], v[224:227], v[30:33]
	v_mfma_f32_16x16x32_bf16 v[26:29], v[184:187], v[224:227], v[26:29]
	v_mfma_f32_16x16x32_bf16 v[14:17], v[174:177], v[236:239], v[14:17]
	v_mfma_f32_16x16x32_bf16 v[10:13], v[184:187], v[236:239], v[10:13]
	v_mfma_f32_16x16x32_bf16 v[54:57], v[188:191], v[204:207], v[54:57]
	v_mfma_f32_16x16x32_bf16 v[50:53], v[196:199], v[204:207], v[50:53]
	v_mfma_f32_16x16x32_bf16 v[38:41], v[188:191], v[212:215], v[38:41]
	v_mfma_f32_16x16x32_bf16 v[34:37], v[196:199], v[212:215], v[34:37]
	v_mfma_f32_16x16x32_bf16 v[22:25], v[188:191], v[220:223], v[22:25]
	v_mfma_f32_16x16x32_bf16 v[18:21], v[196:199], v[220:223], v[18:21]
	v_mfma_f32_16x16x32_bf16 v[6:9], v[188:191], v[228:231], v[6:9]
	v_mfma_f32_16x16x32_bf16 v[2:5], v[196:199], v[228:231], v[2:5]
	v_mfma_f32_16x16x32_bf16 v[54:57], v[192:195], v[208:211], v[54:57]
	v_mfma_f32_16x16x32_bf16 v[50:53], v[200:203], v[208:211], v[50:53]
	v_mfma_f32_16x16x32_bf16 v[38:41], v[192:195], v[216:219], v[38:41]
	v_mfma_f32_16x16x32_bf16 v[34:37], v[200:203], v[216:219], v[34:37]
	v_mfma_f32_16x16x32_bf16 v[22:25], v[192:195], v[224:227], v[22:25]
	v_mfma_f32_16x16x32_bf16 v[18:21], v[200:203], v[224:227], v[18:21]
	v_mfma_f32_16x16x32_bf16 v[6:9], v[192:195], v[236:239], v[6:9]
	s_setprio 0
	v_mfma_f32_16x16x32_bf16 v[2:5], v[200:203], v[236:239], v[2:5]
	s_barrier
	s_add_i32 s68, s68, 2
	s_add_u32 s4, s4, 0x100
	s_addc_u32 s5, s5, 0
	s_add_u32 s63, s63, 0x100
	s_addc_u32 s65, s65, 0
	s_cmp_gt_u32 s68, 61
	s_cbranch_scc0 .LBB0_446
	s_and_b64 vcc, exec, s[20:21]
	s_cbranch_vccz .LBB0_449
	s_barrier

.LBB0_668:
	ds_read_b128 v[154:157], v151
	ds_read_b128 v[158:161], v151 offset:1024
	ds_read_b128 v[162:165], v151 offset:2048
	ds_read_b128 v[166:169], v151 offset:3072
	ds_read_b128 v[170:173], v152
	ds_read_b128 v[174:177], v152 offset:1024
	ds_read_b128 v[178:181], v152 offset:2048
	ds_read_b128 v[182:185], v152 offset:3072
	s_add_u32 s36, s34, 0xfff00080
	s_addc_u32 s37, s35, -1
	s_cmp_eq_u32 s68, 60
	s_cselect_b32 s39, s25, s37
	s_cselect_b32 s38, s61, s36
	s_cselect_b32 s37, s23, s65
	s_cselect_b32 s36, s62, s63
	v_lshl_add_u64 v[148:149], s[34:35], 0, v[140:141]
	s_add_i32 m0, s31, 0xc000
	ds_read_b128 v[186:189], v153
	ds_read_b128 v[190:193], v153 offset:1024
	ds_read_b128 v[194:197], v153 offset:2048
	ds_read_b128 v[198:201], v153 offset:3072
	ds_read_b128 v[202:205], v153 offset:4096
	ds_read_b128 v[206:209], v153 offset:5120
	ds_read_b128 v[210:213], v153 offset:6144
	ds_read_b128 v[214:217], v153 offset:7168
	global_load_lds_dwordx4 v[148:149], off
	v_lshl_add_u64 v[148:149], s[34:35], 0, v[142:143]
	s_add_i32 m0, s31, 0xe000
	s_nop 0
	global_load_lds_dwordx4 v[148:149], off
	s_setprio 1
	s_waitcnt vmcnt(8) lgkmcnt(0)
	s_barrier
	v_mfma_f32_16x16x32_bf16 v[126:129], v[154:157], v[186:189], v[126:129]
	v_mfma_f32_16x16x32_bf16 v[122:125], v[162:165], v[186:189], v[122:125]
	v_mfma_f32_16x16x32_bf16 v[114:117], v[154:157], v[194:197], v[114:117]
	v_mfma_f32_16x16x32_bf16 v[106:109], v[162:165], v[194:197], v[106:109]
	v_mfma_f32_16x16x32_bf16 v[98:101], v[154:157], v[202:205], v[98:101]
	v_mfma_f32_16x16x32_bf16 v[90:93], v[162:165], v[202:205], v[90:93]
	v_mfma_f32_16x16x32_bf16 v[82:85], v[154:157], v[210:213], v[82:85]
	v_mfma_f32_16x16x32_bf16 v[74:77], v[162:165], v[210:213], v[74:77]
	v_mfma_f32_16x16x32_bf16 v[126:129], v[158:161], v[190:193], v[126:129]
	v_mfma_f32_16x16x32_bf16 v[122:125], v[166:169], v[190:193], v[122:125]
	v_mfma_f32_16x16x32_bf16 v[114:117], v[158:161], v[198:201], v[114:117]
	v_mfma_f32_16x16x32_bf16 v[106:109], v[166:169], v[198:201], v[106:109]
	v_mfma_f32_16x16x32_bf16 v[98:101], v[158:161], v[206:209], v[98:101]
	v_mfma_f32_16x16x32_bf16 v[90:93], v[166:169], v[206:209], v[90:93]
	v_mfma_f32_16x16x32_bf16 v[82:85], v[158:161], v[214:217], v[82:85]
	v_mfma_f32_16x16x32_bf16 v[74:77], v[166:169], v[214:217], v[74:77]
	v_mfma_f32_16x16x32_bf16 v[118:121], v[170:173], v[186:189], v[118:121]
	v_mfma_f32_16x16x32_bf16 v[110:113], v[178:181], v[186:189], v[110:113]
	v_mfma_f32_16x16x32_bf16 v[102:105], v[170:173], v[194:197], v[102:105]
	v_mfma_f32_16x16x32_bf16 v[94:97], v[178:181], v[194:197], v[94:97]
	v_mfma_f32_16x16x32_bf16 v[86:89], v[170:173], v[202:205], v[86:89]
	v_mfma_f32_16x16x32_bf16 v[78:81], v[178:181], v[202:205], v[78:81]
	v_mfma_f32_16x16x32_bf16 v[70:73], v[170:173], v[210:213], v[70:73]
	v_mfma_f32_16x16x32_bf16 v[66:69], v[178:181], v[210:213], v[66:69]
	v_mfma_f32_16x16x32_bf16 v[118:121], v[174:177], v[190:193], v[118:121]
	v_mfma_f32_16x16x32_bf16 v[110:113], v[182:185], v[190:193], v[110:113]
	v_mfma_f32_16x16x32_bf16 v[102:105], v[174:177], v[198:201], v[102:105]
	v_mfma_f32_16x16x32_bf16 v[94:97], v[182:185], v[198:201], v[94:97]
	v_mfma_f32_16x16x32_bf16 v[86:89], v[174:177], v[206:209], v[86:89]
	v_mfma_f32_16x16x32_bf16 v[78:81], v[182:185], v[206:209], v[78:81]
	v_mfma_f32_16x16x32_bf16 v[70:73], v[174:177], v[214:217], v[70:73]
	s_setprio 0
	v_mfma_f32_16x16x32_bf16 v[66:69], v[182:185], v[214:217], v[66:69]
	s_barrier
	s_add_i32 s69, s54, s47
	v_lshl_add_u64 v[148:149], s[36:37], 0, v[136:137]
	s_mov_b32 m0, s69
	ds_read_b128 v[186:189], v153 offset:16384
	ds_read_b128 v[190:193], v153 offset:17408
	ds_read_b128 v[194:197], v153 offset:18432
	ds_read_b128 v[198:201], v153 offset:19456
	ds_read_b128 v[202:205], v153 offset:20480
	ds_read_b128 v[206:209], v153 offset:21504
	ds_read_b128 v[210:213], v153 offset:22528
	ds_read_b128 v[214:217], v153 offset:23552
	global_load_lds_dwordx4 v[148:149], off
	s_add_i32 m0, s69, 0x2000
	s_add_u32 s70, s36, 0x100000
	v_lshl_add_u64 v[218:219], s[36:37], 0, v[132:133]
	s_addc_u32 s71, s37, 0
	s_add_i32 s69, s55, s47
	global_load_lds_dwordx4 v[218:219], off
	v_lshl_add_u64 v[220:221], s[70:71], 0, v[136:137]
	s_mov_b32 m0, s69
	v_lshl_add_u64 v[222:223], s[38:39], 0, v[134:135]
	global_load_lds_dwordx4 v[220:221], off
	v_lshl_add_u64 v[220:221], s[70:71], 0, v[132:133]
	s_add_i32 m0, s69, 0x2000
	s_nop 0
	global_load_lds_dwordx4 v[220:221], off
	v_lshl_add_u64 v[220:221], s[38:39], 0, v[138:139]
	s_mov_b32 m0, s31
	s_nop 0
	global_load_lds_dwordx4 v[220:221], off
	s_mov_b32 m0, s48
	s_nop 0
	global_load_lds_dwordx4 v[222:223], off
	s_setprio 1
	s_waitcnt vmcnt(8) lgkmcnt(0)
	s_barrier
	v_mfma_f32_16x16x32_bf16 v[62:65], v[154:157], v[186:189], v[62:65]
	v_mfma_f32_16x16x32_bf16 v[58:61], v[162:165], v[186:189], v[58:61]
	v_mfma_f32_16x16x32_bf16 v[50:53], v[154:157], v[194:197], v[50:53]
	v_mfma_f32_16x16x32_bf16 v[42:45], v[162:165], v[194:197], v[42:45]
	v_mfma_f32_16x16x32_bf16 v[34:37], v[154:157], v[202:205], v[34:37]
	v_mfma_f32_16x16x32_bf16 v[26:29], v[162:165], v[202:205], v[26:29]
	v_mfma_f32_16x16x32_bf16 v[18:21], v[154:157], v[210:213], v[18:21]
	v_mfma_f32_16x16x32_bf16 v[10:13], v[162:165], v[210:213], v[10:13]
	v_mfma_f32_16x16x32_bf16 v[62:65], v[158:161], v[190:193], v[62:65]
	v_mfma_f32_16x16x32_bf16 v[58:61], v[166:169], v[190:193], v[58:61]
	v_mfma_f32_16x16x32_bf16 v[50:53], v[158:161], v[198:201], v[50:53]
	v_mfma_f32_16x16x32_bf16 v[42:45], v[166:169], v[198:201], v[42:45]
	v_mfma_f32_16x16x32_bf16 v[34:37], v[158:161], v[206:209], v[34:37]
	v_mfma_f32_16x16x32_bf16 v[26:29], v[166:169], v[206:209], v[26:29]
	v_mfma_f32_16x16x32_bf16 v[18:21], v[158:161], v[214:217], v[18:21]
	v_mfma_f32_16x16x32_bf16 v[10:13], v[166:169], v[214:217], v[10:13]
	v_mfma_f32_16x16x32_bf16 v[54:57], v[170:173], v[186:189], v[54:57]
	v_mfma_f32_16x16x32_bf16 v[46:49], v[178:181], v[186:189], v[46:49]
	v_mfma_f32_16x16x32_bf16 v[38:41], v[170:173], v[194:197], v[38:41]
	v_mfma_f32_16x16x32_bf16 v[30:33], v[178:181], v[194:197], v[30:33]
	v_mfma_f32_16x16x32_bf16 v[22:25], v[170:173], v[202:205], v[22:25]
	v_mfma_f32_16x16x32_bf16 v[14:17], v[178:181], v[202:205], v[14:17]
	v_mfma_f32_16x16x32_bf16 v[6:9], v[170:173], v[210:213], v[6:9]
	v_mfma_f32_16x16x32_bf16 v[2:5], v[178:181], v[210:213], v[2:5]
	v_mfma_f32_16x16x32_bf16 v[54:57], v[174:177], v[190:193], v[54:57]
	v_mfma_f32_16x16x32_bf16 v[46:49], v[182:185], v[190:193], v[46:49]
	v_mfma_f32_16x16x32_bf16 v[38:41], v[174:177], v[198:201], v[38:41]
	v_mfma_f32_16x16x32_bf16 v[30:33], v[182:185], v[198:201], v[30:33]
	v_mfma_f32_16x16x32_bf16 v[22:25], v[174:177], v[206:209], v[22:25]
	v_mfma_f32_16x16x32_bf16 v[14:17], v[182:185], v[206:209], v[14:17]
	v_mfma_f32_16x16x32_bf16 v[6:9], v[174:177], v[214:217], v[6:9]
	s_setprio 0
	v_mfma_f32_16x16x32_bf16 v[2:5], v[182:185], v[214:217], v[2:5]
	s_barrier
	s_add_i32 s69, 0, 0x18000
	s_add_i32 s70, 0, 0x1c000
	v_add_u32_e32 v166, s69, v131
	v_add_u32_e32 v182, s70, v131
	ds_read_b128 v[154:157], v166
	ds_read_b128 v[158:161], v166 offset:1024
	ds_read_b128 v[162:165], v166 offset:2048
	ds_read_b128 v[166:169], v166 offset:3072
	ds_read_b128 v[170:173], v182
	ds_read_b128 v[174:177], v182 offset:1024
	ds_read_b128 v[178:181], v182 offset:2048
	ds_read_b128 v[182:185], v182 offset:3072
	s_add_u32 s38, s38, 0x100000
	s_addc_u32 s39, s39, 0
	s_mov_b32 m0, s49
	v_lshl_add_u64 v[224:225], s[38:39], 0, v[138:139]
	ds_read_b128 v[186:189], v153 offset:32768
	ds_read_b128 v[190:193], v153 offset:33792
	ds_read_b128 v[194:197], v153 offset:34816
	ds_read_b128 v[198:201], v153 offset:35840
	ds_read_b128 v[202:205], v153 offset:36864
	ds_read_b128 v[206:209], v153 offset:37888
	ds_read_b128 v[210:213], v153 offset:38912
	ds_read_b128 v[214:217], v153 offset:39936
	global_load_lds_dwordx4 v[224:225], off
	v_lshl_add_u64 v[224:225], s[38:39], 0, v[134:135]
	s_mov_b32 m0, s50
	s_nop 0
	global_load_lds_dwordx4 v[224:225], off
	s_setprio 1
	s_waitcnt vmcnt(8) lgkmcnt(0)
	s_barrier
	v_mfma_f32_16x16x32_bf16 v[126:129], v[154:157], v[186:189], v[126:129]
	v_mfma_f32_16x16x32_bf16 v[122:125], v[162:165], v[186:189], v[122:125]
	v_mfma_f32_16x16x32_bf16 v[114:117], v[154:157], v[194:197], v[114:117]
	v_mfma_f32_16x16x32_bf16 v[106:109], v[162:165], v[194:197], v[106:109]
	v_mfma_f32_16x16x32_bf16 v[98:101], v[154:157], v[202:205], v[98:101]
	v_mfma_f32_16x16x32_bf16 v[90:93], v[162:165], v[202:205], v[90:93]
	v_mfma_f32_16x16x32_bf16 v[82:85], v[154:157], v[210:213], v[82:85]
	v_mfma_f32_16x16x32_bf16 v[74:77], v[162:165], v[210:213], v[74:77]
	v_mfma_f32_16x16x32_bf16 v[126:129], v[158:161], v[190:193], v[126:129]
	v_mfma_f32_16x16x32_bf16 v[122:125], v[166:169], v[190:193], v[122:125]
	v_mfma_f32_16x16x32_bf16 v[114:117], v[158:161], v[198:201], v[114:117]
	v_mfma_f32_16x16x32_bf16 v[106:109], v[166:169], v[198:201], v[106:109]
	v_mfma_f32_16x16x32_bf16 v[98:101], v[158:161], v[206:209], v[98:101]
	v_mfma_f32_16x16x32_bf16 v[90:93], v[166:169], v[206:209], v[90:93]
	v_mfma_f32_16x16x32_bf16 v[82:85], v[158:161], v[214:217], v[82:85]
	v_mfma_f32_16x16x32_bf16 v[74:77], v[166:169], v[214:217], v[74:77]
	v_mfma_f32_16x16x32_bf16 v[118:121], v[170:173], v[186:189], v[118:121]
	v_mfma_f32_16x16x32_bf16 v[110:113], v[178:181], v[186:189], v[110:113]
	v_mfma_f32_16x16x32_bf16 v[102:105], v[170:173], v[194:197], v[102:105]
	v_mfma_f32_16x16x32_bf16 v[94:97], v[178:181], v[194:197], v[94:97]
	v_mfma_f32_16x16x32_bf16 v[86:89], v[170:173], v[202:205], v[86:89]
	v_mfma_f32_16x16x32_bf16 v[78:81], v[178:181], v[202:205], v[78:81]
	v_mfma_f32_16x16x32_bf16 v[70:73], v[170:173], v[210:213], v[70:73]
	v_mfma_f32_16x16x32_bf16 v[66:69], v[178:181], v[210:213], v[66:69]
	v_mfma_f32_16x16x32_bf16 v[118:121], v[174:177], v[190:193], v[118:121]
	v_mfma_f32_16x16x32_bf16 v[110:113], v[182:185], v[190:193], v[110:113]
	v_mfma_f32_16x16x32_bf16 v[102:105], v[174:177], v[198:201], v[102:105]
	v_mfma_f32_16x16x32_bf16 v[94:97], v[182:185], v[198:201], v[94:97]
	v_mfma_f32_16x16x32_bf16 v[86:89], v[174:177], v[206:209], v[86:89]
	v_mfma_f32_16x16x32_bf16 v[78:81], v[182:185], v[206:209], v[78:81]
	v_mfma_f32_16x16x32_bf16 v[70:73], v[174:177], v[214:217], v[70:73]
	s_setprio 0
	v_mfma_f32_16x16x32_bf16 v[66:69], v[182:185], v[214:217], v[66:69]
	s_barrier
	s_add_i32 s38, s69, s47
	v_lshl_add_u64 v[148:149], v[148:149], 0, s[8:9]
	s_mov_b32 m0, s38
	ds_read_b128 v[186:189], v153 offset:49152
	ds_read_b128 v[190:193], v153 offset:50176
	ds_read_b128 v[194:197], v153 offset:51200
	ds_read_b128 v[198:201], v153 offset:52224
	ds_read_b128 v[202:205], v153 offset:53248
	ds_read_b128 v[206:209], v153 offset:54272
	ds_read_b128 v[210:213], v153 offset:55296
	ds_read_b128 v[214:217], v153 offset:56320
	global_load_lds_dwordx4 v[148:149], off
	s_add_i32 m0, s38, 0x2000
	s_add_u32 s36, s36, 0x100080
	v_lshl_add_u64 v[148:149], v[218:219], 0, s[8:9]
	s_addc_u32 s37, s37, 0
	s_add_i32 s38, s70, s47
	global_load_lds_dwordx4 v[148:149], off
	v_lshl_add_u64 v[148:149], s[36:37], 0, v[136:137]
	s_mov_b32 m0, s38
	s_nop 0
	global_load_lds_dwordx4 v[148:149], off
	v_lshl_add_u64 v[148:149], s[36:37], 0, v[132:133]
	s_add_i32 m0, s38, 0x2000
	s_nop 0
	global_load_lds_dwordx4 v[148:149], off
	v_lshl_add_u64 v[148:149], v[220:221], 0, s[8:9]
	s_mov_b32 m0, s52
	s_nop 0
	global_load_lds_dwordx4 v[148:149], off
	v_lshl_add_u64 v[148:149], v[222:223], 0, s[8:9]
	s_mov_b32 m0, s53
	s_nop 0
	global_load_lds_dwordx4 v[148:149], off
	s_setprio 1
	s_waitcnt vmcnt(8) lgkmcnt(0)
	s_barrier
	v_mfma_f32_16x16x32_bf16 v[62:65], v[154:157], v[186:189], v[62:65]
	v_mfma_f32_16x16x32_bf16 v[58:61], v[162:165], v[186:189], v[58:61]
	v_mfma_f32_16x16x32_bf16 v[50:53], v[154:157], v[194:197], v[50:53]
	v_mfma_f32_16x16x32_bf16 v[42:45], v[162:165], v[194:197], v[42:45]
	v_mfma_f32_16x16x32_bf16 v[34:37], v[154:157], v[202:205], v[34:37]
	v_mfma_f32_16x16x32_bf16 v[26:29], v[162:165], v[202:205], v[26:29]
	v_mfma_f32_16x16x32_bf16 v[18:21], v[154:157], v[210:213], v[18:21]
	v_mfma_f32_16x16x32_bf16 v[10:13], v[162:165], v[210:213], v[10:13]
	v_mfma_f32_16x16x32_bf16 v[62:65], v[158:161], v[190:193], v[62:65]
	v_mfma_f32_16x16x32_bf16 v[58:61], v[166:169], v[190:193], v[58:61]
	v_mfma_f32_16x16x32_bf16 v[50:53], v[158:161], v[198:201], v[50:53]
	v_mfma_f32_16x16x32_bf16 v[42:45], v[166:169], v[198:201], v[42:45]
	v_mfma_f32_16x16x32_bf16 v[34:37], v[158:161], v[206:209], v[34:37]
	v_mfma_f32_16x16x32_bf16 v[26:29], v[166:169], v[206:209], v[26:29]
	v_mfma_f32_16x16x32_bf16 v[18:21], v[158:161], v[214:217], v[18:21]
	v_mfma_f32_16x16x32_bf16 v[10:13], v[166:169], v[214:217], v[10:13]
	v_mfma_f32_16x16x32_bf16 v[54:57], v[170:173], v[186:189], v[54:57]
	v_mfma_f32_16x16x32_bf16 v[46:49], v[178:181], v[186:189], v[46:49]
	v_mfma_f32_16x16x32_bf16 v[38:41], v[170:173], v[194:197], v[38:41]
	v_mfma_f32_16x16x32_bf16 v[30:33], v[178:181], v[194:197], v[30:33]
	v_mfma_f32_16x16x32_bf16 v[22:25], v[170:173], v[202:205], v[22:25]
	v_mfma_f32_16x16x32_bf16 v[14:17], v[178:181], v[202:205], v[14:17]
	v_mfma_f32_16x16x32_bf16 v[6:9], v[170:173], v[210:213], v[6:9]
	v_mfma_f32_16x16x32_bf16 v[2:5], v[178:181], v[210:213], v[2:5]
	v_mfma_f32_16x16x32_bf16 v[54:57], v[174:177], v[190:193], v[54:57]
	v_mfma_f32_16x16x32_bf16 v[46:49], v[182:185], v[190:193], v[46:49]
	v_mfma_f32_16x16x32_bf16 v[38:41], v[174:177], v[198:201], v[38:41]
	v_mfma_f32_16x16x32_bf16 v[30:33], v[182:185], v[198:201], v[30:33]
	v_mfma_f32_16x16x32_bf16 v[22:25], v[174:177], v[206:209], v[22:25]
	v_mfma_f32_16x16x32_bf16 v[14:17], v[182:185], v[206:209], v[14:17]
	v_mfma_f32_16x16x32_bf16 v[6:9], v[174:177], v[214:217], v[6:9]
	s_setprio 0
	v_mfma_f32_16x16x32_bf16 v[2:5], v[182:185], v[214:217], v[2:5]
	s_barrier
	s_add_i32 s68, s68, 2
	s_add_u32 s34, s34, 0x100
	s_addc_u32 s35, s35, 0
	s_add_u32 s63, s63, 0x100
	s_addc_u32 s65, s65, 0
	s_cmp_gt_u32 s68, 61
	s_cbranch_scc0 .LBB0_668
	s_and_b64 vcc, exec, s[12:13]
	s_cbranch_vccz .LBB0_671
	s_barrier

.LBB0_845:
	ds_read_b128 v[130:133], v238
	ds_read_b128 v[134:137], v238 offset:1024
	ds_read_b128 v[138:141], v238 offset:2048
	ds_read_b128 v[142:145], v238 offset:3072
	ds_read_b128 v[146:149], v239
	ds_read_b128 v[150:153], v239 offset:1024
	ds_read_b128 v[154:157], v239 offset:2048
	ds_read_b128 v[158:161], v239 offset:3072
	s_add_u32 s56, s2, 0x100
	s_addc_u32 s57, s3, 0
	s_cmp_eq_u32 s92, 28
	s_cselect_b32 s61, s49, s57
	s_cselect_b32 s60, s88, s56
	s_cselect_b32 s59, s47, s91
	s_cselect_b32 s58, s89, s90
	v_lshl_add_u64 v[194:195], s[2:3], 0, v[210:211]
	s_add_i32 m0, s55, 0xc000
	ds_read_b128 v[162:165], v240
	ds_read_b128 v[166:169], v240 offset:1024
	ds_read_b128 v[170:173], v240 offset:2048
	ds_read_b128 v[174:177], v240 offset:3072
	ds_read_b128 v[178:181], v240 offset:4096
	ds_read_b128 v[182:185], v240 offset:5120
	ds_read_b128 v[186:189], v240 offset:6144
	ds_read_b128 v[190:193], v240 offset:7168
	global_load_lds_dwordx4 v[194:195], off
	v_lshl_add_u64 v[194:195], s[2:3], 0, v[212:213]
	s_add_i32 m0, s55, 0xe000
	s_nop 0
	global_load_lds_dwordx4 v[194:195], off
	s_setprio 1
	s_waitcnt vmcnt(8) lgkmcnt(0)
	s_barrier
	v_mfma_i32_16x16x64_i8 v[126:129], v[130:133], v[162:165], v[126:129]
	v_mfma_i32_16x16x64_i8 v[122:125], v[138:141], v[162:165], v[122:125]
	v_mfma_i32_16x16x64_i8 v[118:121], v[130:133], v[170:173], v[118:121]
	v_mfma_i32_16x16x64_i8 v[110:113], v[138:141], v[170:173], v[110:113]
	v_mfma_i32_16x16x64_i8 v[78:81], v[130:133], v[178:181], v[78:81]
	v_mfma_i32_16x16x64_i8 v[30:33], v[138:141], v[178:181], v[30:33]
	v_mfma_i32_16x16x64_i8 v[74:77], v[130:133], v[186:189], v[74:77]
	v_mfma_i32_16x16x64_i8 v[26:29], v[138:141], v[186:189], v[26:29]
	v_mfma_i32_16x16x64_i8 v[126:129], v[134:137], v[166:169], v[126:129]
	v_mfma_i32_16x16x64_i8 v[122:125], v[142:145], v[166:169], v[122:125]
	v_mfma_i32_16x16x64_i8 v[118:121], v[134:137], v[174:177], v[118:121]
	v_mfma_i32_16x16x64_i8 v[110:113], v[142:145], v[174:177], v[110:113]
	v_mfma_i32_16x16x64_i8 v[78:81], v[134:137], v[182:185], v[78:81]
	v_mfma_i32_16x16x64_i8 v[30:33], v[142:145], v[182:185], v[30:33]
	v_mfma_i32_16x16x64_i8 v[74:77], v[134:137], v[190:193], v[74:77]
	v_mfma_i32_16x16x64_i8 v[26:29], v[142:145], v[190:193], v[26:29]
	v_mfma_i32_16x16x64_i8 v[102:105], v[146:149], v[162:165], v[102:105]
	v_mfma_i32_16x16x64_i8 v[98:101], v[154:157], v[162:165], v[98:101]
	v_mfma_i32_16x16x64_i8 v[94:97], v[146:149], v[170:173], v[94:97]
	v_mfma_i32_16x16x64_i8 v[90:93], v[154:157], v[170:173], v[90:93]
	v_mfma_i32_16x16x64_i8 v[70:73], v[146:149], v[178:181], v[70:73]
	v_mfma_i32_16x16x64_i8 v[22:25], v[154:157], v[178:181], v[22:25]
	v_mfma_i32_16x16x64_i8 v[66:69], v[146:149], v[186:189], v[66:69]
	v_mfma_i32_16x16x64_i8 v[18:21], v[154:157], v[186:189], v[18:21]
	v_mfma_i32_16x16x64_i8 v[102:105], v[150:153], v[166:169], v[102:105]
	v_mfma_i32_16x16x64_i8 v[98:101], v[158:161], v[166:169], v[98:101]
	v_mfma_i32_16x16x64_i8 v[94:97], v[150:153], v[174:177], v[94:97]
	v_mfma_i32_16x16x64_i8 v[90:93], v[158:161], v[174:177], v[90:93]
	v_mfma_i32_16x16x64_i8 v[70:73], v[150:153], v[182:185], v[70:73]
	v_mfma_i32_16x16x64_i8 v[22:25], v[158:161], v[182:185], v[22:25]
	v_mfma_i32_16x16x64_i8 v[66:69], v[150:153], v[190:193], v[66:69]
	s_setprio 0
	v_mfma_i32_16x16x64_i8 v[18:21], v[158:161], v[190:193], v[18:21]
	s_barrier
	s_add_i32 s2, s84, s65
	v_lshl_add_u64 v[194:195], s[58:59], 0, v[206:207]
	s_mov_b32 m0, s2
	ds_read_b128 v[162:165], v240 offset:16384
	ds_read_b128 v[166:169], v240 offset:17408
	ds_read_b128 v[170:173], v240 offset:18432
	ds_read_b128 v[174:177], v240 offset:19456
	ds_read_b128 v[178:181], v240 offset:20480
	ds_read_b128 v[182:185], v240 offset:21504
	ds_read_b128 v[186:189], v240 offset:22528
	ds_read_b128 v[190:193], v240 offset:23552
	global_load_lds_dwordx4 v[194:195], off
	s_add_i32 m0, s2, 0x2000
	s_add_u32 s2, s58, 0x80000
	v_lshl_add_u64 v[196:197], s[58:59], 0, v[202:203]
	s_addc_u32 s3, s59, 0
	s_add_i32 s93, s85, s65
	global_load_lds_dwordx4 v[196:197], off
	v_lshl_add_u64 v[198:199], s[2:3], 0, v[206:207]
	s_mov_b32 m0, s93
	v_lshl_add_u64 v[200:201], s[60:61], 0, v[204:205]
	global_load_lds_dwordx4 v[198:199], off
	v_lshl_add_u64 v[198:199], s[2:3], 0, v[202:203]
	s_add_i32 m0, s93, 0x2000
	s_nop 0
	global_load_lds_dwordx4 v[198:199], off
	v_lshl_add_u64 v[198:199], s[60:61], 0, v[208:209]
	s_mov_b32 m0, s55
	s_nop 0
	global_load_lds_dwordx4 v[198:199], off
	s_mov_b32 m0, s69
	s_nop 0
	global_load_lds_dwordx4 v[200:201], off
	s_setprio 1
	s_waitcnt vmcnt(8) lgkmcnt(0)
	s_barrier
	v_mfma_i32_16x16x64_i8 v[62:65], v[130:133], v[162:165], v[62:65]
	v_mfma_i32_16x16x64_i8 v[14:17], v[138:141], v[162:165], v[14:17]
	v_mfma_i32_16x16x64_i8 v[58:61], v[130:133], v[170:173], v[58:61]
	v_mfma_i32_16x16x64_i8 v[10:13], v[138:141], v[170:173], v[10:13]
	v_mfma_i32_16x16x64_i8 v[114:117], v[130:133], v[178:181], v[114:117]
	v_mfma_i32_16x16x64_i8 v[106:109], v[138:141], v[178:181], v[106:109]
	v_mfma_i32_16x16x64_i8 v[86:89], v[130:133], v[186:189], v[86:89]
	v_mfma_i32_16x16x64_i8 v[82:85], v[138:141], v[186:189], v[82:85]
	v_mfma_i32_16x16x64_i8 v[62:65], v[134:137], v[166:169], v[62:65]
	v_mfma_i32_16x16x64_i8 v[14:17], v[142:145], v[166:169], v[14:17]
	v_mfma_i32_16x16x64_i8 v[58:61], v[134:137], v[174:177], v[58:61]
	v_mfma_i32_16x16x64_i8 v[10:13], v[142:145], v[174:177], v[10:13]
	v_mfma_i32_16x16x64_i8 v[114:117], v[134:137], v[182:185], v[114:117]
	v_mfma_i32_16x16x64_i8 v[106:109], v[142:145], v[182:185], v[106:109]
	v_mfma_i32_16x16x64_i8 v[86:89], v[134:137], v[190:193], v[86:89]
	v_mfma_i32_16x16x64_i8 v[82:85], v[142:145], v[190:193], v[82:85]
	v_mfma_i32_16x16x64_i8 v[50:53], v[146:149], v[162:165], v[50:53]
	v_mfma_i32_16x16x64_i8 v[6:9], v[154:157], v[162:165], v[6:9]
	v_mfma_i32_16x16x64_i8 v[42:45], v[146:149], v[170:173], v[42:45]
	v_mfma_i32_16x16x64_i8 v[2:5], v[154:157], v[170:173], v[2:5]
	v_mfma_i32_16x16x64_i8 v[54:57], v[146:149], v[178:181], v[54:57]
	v_mfma_i32_16x16x64_i8 v[46:49], v[154:157], v[178:181], v[46:49]
	v_mfma_i32_16x16x64_i8 v[38:41], v[146:149], v[186:189], v[38:41]
	v_mfma_i32_16x16x64_i8 v[34:37], v[154:157], v[186:189], v[34:37]
	v_mfma_i32_16x16x64_i8 v[50:53], v[150:153], v[166:169], v[50:53]
	v_mfma_i32_16x16x64_i8 v[6:9], v[158:161], v[166:169], v[6:9]
	v_mfma_i32_16x16x64_i8 v[42:45], v[150:153], v[174:177], v[42:45]
	v_mfma_i32_16x16x64_i8 v[2:5], v[158:161], v[174:177], v[2:5]
	v_mfma_i32_16x16x64_i8 v[54:57], v[150:153], v[182:185], v[54:57]
	v_mfma_i32_16x16x64_i8 v[46:49], v[158:161], v[182:185], v[46:49]
	v_mfma_i32_16x16x64_i8 v[38:41], v[150:153], v[190:193], v[38:41]
	s_setprio 0
	v_mfma_i32_16x16x64_i8 v[34:37], v[158:161], v[190:193], v[34:37]
	s_barrier
	s_add_i32 s93, 0, 0x18000
	s_add_i32 s94, 0, 0x1c000
	v_add_u32_e32 v142, s93, v237
	v_add_u32_e32 v158, s94, v237
	ds_read_b128 v[130:133], v142
	ds_read_b128 v[134:137], v142 offset:1024
	ds_read_b128 v[138:141], v142 offset:2048
	ds_read_b128 v[142:145], v142 offset:3072
	ds_read_b128 v[146:149], v158
	ds_read_b128 v[150:153], v158 offset:1024
	ds_read_b128 v[154:157], v158 offset:2048
	ds_read_b128 v[158:161], v158 offset:3072
	s_add_u32 s2, s60, 0x4000
	s_addc_u32 s3, s61, 0
	s_mov_b32 m0, s70
	v_lshl_add_u64 v[220:221], s[2:3], 0, v[208:209]
	ds_read_b128 v[162:165], v240 offset:32768
	ds_read_b128 v[166:169], v240 offset:33792
	ds_read_b128 v[170:173], v240 offset:34816
	ds_read_b128 v[174:177], v240 offset:35840
	ds_read_b128 v[178:181], v240 offset:36864
	ds_read_b128 v[182:185], v240 offset:37888
	ds_read_b128 v[186:189], v240 offset:38912
	ds_read_b128 v[190:193], v240 offset:39936
	global_load_lds_dwordx4 v[220:221], off
	v_lshl_add_u64 v[220:221], s[2:3], 0, v[204:205]
	s_mov_b32 m0, s71
	s_nop 0
	global_load_lds_dwordx4 v[220:221], off
	s_setprio 1
	s_waitcnt vmcnt(8) lgkmcnt(0)
	s_barrier
	v_mfma_i32_16x16x64_i8 v[126:129], v[130:133], v[162:165], v[126:129]
	v_mfma_i32_16x16x64_i8 v[122:125], v[138:141], v[162:165], v[122:125]
	v_mfma_i32_16x16x64_i8 v[118:121], v[130:133], v[170:173], v[118:121]
	v_mfma_i32_16x16x64_i8 v[110:113], v[138:141], v[170:173], v[110:113]
	v_mfma_i32_16x16x64_i8 v[78:81], v[130:133], v[178:181], v[78:81]
	v_mfma_i32_16x16x64_i8 v[30:33], v[138:141], v[178:181], v[30:33]
	v_mfma_i32_16x16x64_i8 v[74:77], v[130:133], v[186:189], v[74:77]
	v_mfma_i32_16x16x64_i8 v[26:29], v[138:141], v[186:189], v[26:29]
	v_mfma_i32_16x16x64_i8 v[126:129], v[134:137], v[166:169], v[126:129]
	v_mfma_i32_16x16x64_i8 v[122:125], v[142:145], v[166:169], v[122:125]
	v_mfma_i32_16x16x64_i8 v[118:121], v[134:137], v[174:177], v[118:121]
	v_mfma_i32_16x16x64_i8 v[110:113], v[142:145], v[174:177], v[110:113]
	v_mfma_i32_16x16x64_i8 v[78:81], v[134:137], v[182:185], v[78:81]
	v_mfma_i32_16x16x64_i8 v[30:33], v[142:145], v[182:185], v[30:33]
	v_mfma_i32_16x16x64_i8 v[74:77], v[134:137], v[190:193], v[74:77]
	v_mfma_i32_16x16x64_i8 v[26:29], v[142:145], v[190:193], v[26:29]
	v_mfma_i32_16x16x64_i8 v[102:105], v[146:149], v[162:165], v[102:105]
	v_mfma_i32_16x16x64_i8 v[98:101], v[154:157], v[162:165], v[98:101]
	v_mfma_i32_16x16x64_i8 v[94:97], v[146:149], v[170:173], v[94:97]
	v_mfma_i32_16x16x64_i8 v[90:93], v[154:157], v[170:173], v[90:93]
	v_mfma_i32_16x16x64_i8 v[70:73], v[146:149], v[178:181], v[70:73]
	v_mfma_i32_16x16x64_i8 v[22:25], v[154:157], v[178:181], v[22:25]
	v_mfma_i32_16x16x64_i8 v[66:69], v[146:149], v[186:189], v[66:69]
	v_mfma_i32_16x16x64_i8 v[18:21], v[154:157], v[186:189], v[18:21]
	v_mfma_i32_16x16x64_i8 v[102:105], v[150:153], v[166:169], v[102:105]
	v_mfma_i32_16x16x64_i8 v[98:101], v[158:161], v[166:169], v[98:101]
	v_mfma_i32_16x16x64_i8 v[94:97], v[150:153], v[174:177], v[94:97]
	v_mfma_i32_16x16x64_i8 v[90:93], v[158:161], v[174:177], v[90:93]
	v_mfma_i32_16x16x64_i8 v[70:73], v[150:153], v[182:185], v[70:73]
	v_mfma_i32_16x16x64_i8 v[22:25], v[158:161], v[182:185], v[22:25]
	v_mfma_i32_16x16x64_i8 v[66:69], v[150:153], v[190:193], v[66:69]
	s_setprio 0
	v_mfma_i32_16x16x64_i8 v[18:21], v[158:161], v[190:193], v[18:21]
	s_barrier
	s_add_i32 s2, s93, s65
	v_lshl_add_u64 v[194:195], v[194:195], 0, s[36:37]
	s_mov_b32 m0, s2
	ds_read_b128 v[162:165], v240 offset:49152
	ds_read_b128 v[166:169], v240 offset:50176
	ds_read_b128 v[170:173], v240 offset:51200
	ds_read_b128 v[174:177], v240 offset:52224
	ds_read_b128 v[178:181], v240 offset:53248
	ds_read_b128 v[182:185], v240 offset:54272
	ds_read_b128 v[186:189], v240 offset:55296
	ds_read_b128 v[190:193], v240 offset:56320
	global_load_lds_dwordx4 v[194:195], off
	s_add_i32 m0, s2, 0x2000
	s_add_u32 s2, s58, 0x80080
	v_lshl_add_u64 v[194:195], v[196:197], 0, s[36:37]
	s_addc_u32 s3, s59, 0
	s_add_i32 s58, s94, s65
	global_load_lds_dwordx4 v[194:195], off
	v_lshl_add_u64 v[194:195], s[2:3], 0, v[206:207]
	s_mov_b32 m0, s58
	s_nop 0
	global_load_lds_dwordx4 v[194:195], off
	v_lshl_add_u64 v[194:195], s[2:3], 0, v[202:203]
	s_add_i32 m0, s58, 0x2000
	s_nop 0
	global_load_lds_dwordx4 v[194:195], off
	v_lshl_add_u64 v[194:195], v[198:199], 0, s[36:37]
	s_mov_b32 m0, s78
	s_nop 0
	global_load_lds_dwordx4 v[194:195], off
	v_lshl_add_u64 v[194:195], v[200:201], 0, s[36:37]
	s_mov_b32 m0, s79
	s_nop 0
	global_load_lds_dwordx4 v[194:195], off
	s_setprio 1
	s_waitcnt vmcnt(8) lgkmcnt(0)
	s_barrier
	v_mfma_i32_16x16x64_i8 v[62:65], v[130:133], v[162:165], v[62:65]
	v_mfma_i32_16x16x64_i8 v[14:17], v[138:141], v[162:165], v[14:17]
	v_mfma_i32_16x16x64_i8 v[58:61], v[130:133], v[170:173], v[58:61]
	v_mfma_i32_16x16x64_i8 v[10:13], v[138:141], v[170:173], v[10:13]
	v_mfma_i32_16x16x64_i8 v[114:117], v[130:133], v[178:181], v[114:117]
	v_mfma_i32_16x16x64_i8 v[106:109], v[138:141], v[178:181], v[106:109]
	v_mfma_i32_16x16x64_i8 v[86:89], v[130:133], v[186:189], v[86:89]
	v_mfma_i32_16x16x64_i8 v[82:85], v[138:141], v[186:189], v[82:85]
	v_mfma_i32_16x16x64_i8 v[62:65], v[134:137], v[166:169], v[62:65]
	v_mfma_i32_16x16x64_i8 v[14:17], v[142:145], v[166:169], v[14:17]
	v_mfma_i32_16x16x64_i8 v[58:61], v[134:137], v[174:177], v[58:61]
	v_mfma_i32_16x16x64_i8 v[10:13], v[142:145], v[174:177], v[10:13]
	v_mfma_i32_16x16x64_i8 v[114:117], v[134:137], v[182:185], v[114:117]
	v_mfma_i32_16x16x64_i8 v[106:109], v[142:145], v[182:185], v[106:109]
	v_mfma_i32_16x16x64_i8 v[86:89], v[134:137], v[190:193], v[86:89]
	v_mfma_i32_16x16x64_i8 v[82:85], v[142:145], v[190:193], v[82:85]
	v_mfma_i32_16x16x64_i8 v[50:53], v[146:149], v[162:165], v[50:53]
	v_mfma_i32_16x16x64_i8 v[6:9], v[154:157], v[162:165], v[6:9]
	v_mfma_i32_16x16x64_i8 v[42:45], v[146:149], v[170:173], v[42:45]
	v_mfma_i32_16x16x64_i8 v[2:5], v[154:157], v[170:173], v[2:5]
	v_mfma_i32_16x16x64_i8 v[54:57], v[146:149], v[178:181], v[54:57]
	v_mfma_i32_16x16x64_i8 v[46:49], v[154:157], v[178:181], v[46:49]
	v_mfma_i32_16x16x64_i8 v[38:41], v[146:149], v[186:189], v[38:41]
	v_mfma_i32_16x16x64_i8 v[34:37], v[154:157], v[186:189], v[34:37]
	v_mfma_i32_16x16x64_i8 v[50:53], v[150:153], v[166:169], v[50:53]
	v_mfma_i32_16x16x64_i8 v[6:9], v[158:161], v[166:169], v[6:9]
	v_mfma_i32_16x16x64_i8 v[42:45], v[150:153], v[174:177], v[42:45]
	v_mfma_i32_16x16x64_i8 v[2:5], v[158:161], v[174:177], v[2:5]
	v_mfma_i32_16x16x64_i8 v[54:57], v[150:153], v[182:185], v[54:57]
	v_mfma_i32_16x16x64_i8 v[46:49], v[158:161], v[182:185], v[46:49]
	v_mfma_i32_16x16x64_i8 v[38:41], v[150:153], v[190:193], v[38:41]
	s_setprio 0
	v_mfma_i32_16x16x64_i8 v[34:37], v[158:161], v[190:193], v[34:37]
	s_barrier
	s_add_i32 s92, s92, 2
	s_add_u32 s90, s90, 0x100
	s_addc_u32 s91, s91, 0
	s_cmp_gt_u32 s92, 29
	s_mov_b64 s[2:3], s[56:57]
	s_cbranch_scc0 .LBB0_845
	s_and_b64 vcc, exec, s[38:39]
	s_cbranch_vccz .LBB0_848
	s_barrier

.LBB0_1099:
	ds_read_b128 v[130:133], v167
	ds_read_b128 v[134:137], v167 offset:1024
	ds_read_b128 v[138:141], v167 offset:2048
	ds_read_b128 v[142:145], v167 offset:3072
	ds_read_b128 v[170:173], v168
	ds_read_b128 v[174:177], v168 offset:1024
	ds_read_b128 v[178:181], v168 offset:2048
	ds_read_b128 v[182:185], v168 offset:3072
	s_add_u32 s30, s28, 0x100
	s_addc_u32 s31, s29, 0
	s_cmpk_eq_i32 s72, 0x52
	s_cselect_b32 s37, s3, s31
	s_cselect_b32 s36, s2, s30
	s_cselect_b32 s35, s27, s71
	s_cselect_b32 s34, s26, s70
	v_lshl_add_u64 v[162:163], s[28:29], 0, v[154:155]
	s_add_i32 m0, s47, 0xc000
	ds_read_b128 v[186:189], v169
	ds_read_b128 v[190:193], v169 offset:1024
	ds_read_b128 v[194:197], v169 offset:2048
	ds_read_b128 v[198:201], v169 offset:3072
	ds_read_b128 v[202:205], v169 offset:4096
	ds_read_b128 v[206:209], v169 offset:5120
	ds_read_b128 v[210:213], v169 offset:6144
	ds_read_b128 v[214:217], v169 offset:7168
	global_load_lds_dwordx4 v[162:163], off
	v_lshl_add_u64 v[162:163], s[28:29], 0, v[156:157]
	s_add_i32 m0, s47, 0xe000
	s_nop 0
	global_load_lds_dwordx4 v[162:163], off
	s_setprio 1
	s_waitcnt vmcnt(8) lgkmcnt(0)
	s_barrier
	v_mfma_i32_16x16x64_i8 v[126:129], v[130:133], v[186:189], v[126:129]
	v_mfma_i32_16x16x64_i8 v[122:125], v[138:141], v[186:189], v[122:125]
	v_mfma_i32_16x16x64_i8 v[110:113], v[130:133], v[194:197], v[110:113]
	v_mfma_i32_16x16x64_i8 v[106:109], v[138:141], v[194:197], v[106:109]
	v_mfma_i32_16x16x64_i8 v[94:97], v[130:133], v[202:205], v[94:97]
	v_mfma_i32_16x16x64_i8 v[90:93], v[138:141], v[202:205], v[90:93]
	v_mfma_i32_16x16x64_i8 v[78:81], v[130:133], v[210:213], v[78:81]
	v_mfma_i32_16x16x64_i8 v[74:77], v[138:141], v[210:213], v[74:77]
	v_mfma_i32_16x16x64_i8 v[126:129], v[134:137], v[190:193], v[126:129]
	v_mfma_i32_16x16x64_i8 v[122:125], v[142:145], v[190:193], v[122:125]
	v_mfma_i32_16x16x64_i8 v[110:113], v[134:137], v[198:201], v[110:113]
	v_mfma_i32_16x16x64_i8 v[106:109], v[142:145], v[198:201], v[106:109]
	v_mfma_i32_16x16x64_i8 v[94:97], v[134:137], v[206:209], v[94:97]
	v_mfma_i32_16x16x64_i8 v[90:93], v[142:145], v[206:209], v[90:93]
	v_mfma_i32_16x16x64_i8 v[78:81], v[134:137], v[214:217], v[78:81]
	v_mfma_i32_16x16x64_i8 v[74:77], v[142:145], v[214:217], v[74:77]
	v_mfma_i32_16x16x64_i8 v[118:121], v[170:173], v[186:189], v[118:121]
	v_mfma_i32_16x16x64_i8 v[114:117], v[178:181], v[186:189], v[114:117]
	v_mfma_i32_16x16x64_i8 v[102:105], v[170:173], v[194:197], v[102:105]
	v_mfma_i32_16x16x64_i8 v[98:101], v[178:181], v[194:197], v[98:101]
	v_mfma_i32_16x16x64_i8 v[86:89], v[170:173], v[202:205], v[86:89]
	v_mfma_i32_16x16x64_i8 v[82:85], v[178:181], v[202:205], v[82:85]
	v_mfma_i32_16x16x64_i8 v[70:73], v[170:173], v[210:213], v[70:73]
	v_mfma_i32_16x16x64_i8 v[66:69], v[178:181], v[210:213], v[66:69]
	v_mfma_i32_16x16x64_i8 v[118:121], v[174:177], v[190:193], v[118:121]
	v_mfma_i32_16x16x64_i8 v[114:117], v[182:185], v[190:193], v[114:117]
	v_mfma_i32_16x16x64_i8 v[102:105], v[174:177], v[198:201], v[102:105]
	v_mfma_i32_16x16x64_i8 v[98:101], v[182:185], v[198:201], v[98:101]
	v_mfma_i32_16x16x64_i8 v[86:89], v[174:177], v[206:209], v[86:89]
	v_mfma_i32_16x16x64_i8 v[82:85], v[182:185], v[206:209], v[82:85]
	v_mfma_i32_16x16x64_i8 v[70:73], v[174:177], v[214:217], v[70:73]
	s_setprio 0
	v_mfma_i32_16x16x64_i8 v[66:69], v[182:185], v[214:217], v[66:69]
	s_barrier
	s_add_i32 s28, s56, s46
	v_lshl_add_u64 v[162:163], s[34:35], 0, v[150:151]
	s_mov_b32 m0, s28
	ds_read_b128 v[186:189], v169 offset:16384
	ds_read_b128 v[190:193], v169 offset:17408
	ds_read_b128 v[194:197], v169 offset:18432
	ds_read_b128 v[198:201], v169 offset:19456
	ds_read_b128 v[202:205], v169 offset:20480
	ds_read_b128 v[206:209], v169 offset:21504
	ds_read_b128 v[210:213], v169 offset:22528
	ds_read_b128 v[214:217], v169 offset:23552
	global_load_lds_dwordx4 v[162:163], off
	s_add_i32 m0, s28, 0x2000
	s_add_u32 s28, s34, 0x158000
	v_lshl_add_u64 v[218:219], s[34:35], 0, v[146:147]
	s_addc_u32 s29, s35, 0
	s_add_i32 s73, s57, s46
	global_load_lds_dwordx4 v[218:219], off
	v_lshl_add_u64 v[220:221], s[28:29], 0, v[150:151]
	s_mov_b32 m0, s73
	v_lshl_add_u64 v[222:223], s[36:37], 0, v[148:149]
	global_load_lds_dwordx4 v[220:221], off
	v_lshl_add_u64 v[220:221], s[28:29], 0, v[146:147]
	s_add_i32 m0, s73, 0x2000
	s_nop 0
	global_load_lds_dwordx4 v[220:221], off
	v_lshl_add_u64 v[220:221], s[36:37], 0, v[152:153]
	s_mov_b32 m0, s47
	s_nop 0
	global_load_lds_dwordx4 v[220:221], off
	s_mov_b32 m0, s48
	s_nop 0
	global_load_lds_dwordx4 v[222:223], off
	s_setprio 1
	s_waitcnt vmcnt(8) lgkmcnt(0)
	s_barrier
	v_mfma_i32_16x16x64_i8 v[62:65], v[130:133], v[186:189], v[62:65]
	v_mfma_i32_16x16x64_i8 v[58:61], v[138:141], v[186:189], v[58:61]
	v_mfma_i32_16x16x64_i8 v[46:49], v[130:133], v[194:197], v[46:49]
	v_mfma_i32_16x16x64_i8 v[42:45], v[138:141], v[194:197], v[42:45]
	v_mfma_i32_16x16x64_i8 v[30:33], v[130:133], v[202:205], v[30:33]
	v_mfma_i32_16x16x64_i8 v[26:29], v[138:141], v[202:205], v[26:29]
	v_mfma_i32_16x16x64_i8 v[14:17], v[130:133], v[210:213], v[14:17]
	v_mfma_i32_16x16x64_i8 v[10:13], v[138:141], v[210:213], v[10:13]
	v_mfma_i32_16x16x64_i8 v[62:65], v[134:137], v[190:193], v[62:65]
	v_mfma_i32_16x16x64_i8 v[58:61], v[142:145], v[190:193], v[58:61]
	v_mfma_i32_16x16x64_i8 v[46:49], v[134:137], v[198:201], v[46:49]
	v_mfma_i32_16x16x64_i8 v[42:45], v[142:145], v[198:201], v[42:45]
	v_mfma_i32_16x16x64_i8 v[30:33], v[134:137], v[206:209], v[30:33]
	v_mfma_i32_16x16x64_i8 v[26:29], v[142:145], v[206:209], v[26:29]
	v_mfma_i32_16x16x64_i8 v[14:17], v[134:137], v[214:217], v[14:17]
	v_mfma_i32_16x16x64_i8 v[10:13], v[142:145], v[214:217], v[10:13]
	v_mfma_i32_16x16x64_i8 v[54:57], v[170:173], v[186:189], v[54:57]
	v_mfma_i32_16x16x64_i8 v[50:53], v[178:181], v[186:189], v[50:53]
	v_mfma_i32_16x16x64_i8 v[38:41], v[170:173], v[194:197], v[38:41]
	v_mfma_i32_16x16x64_i8 v[34:37], v[178:181], v[194:197], v[34:37]
	v_mfma_i32_16x16x64_i8 v[22:25], v[170:173], v[202:205], v[22:25]
	v_mfma_i32_16x16x64_i8 v[18:21], v[178:181], v[202:205], v[18:21]
	v_mfma_i32_16x16x64_i8 v[6:9], v[170:173], v[210:213], v[6:9]
	v_mfma_i32_16x16x64_i8 v[2:5], v[178:181], v[210:213], v[2:5]
	v_mfma_i32_16x16x64_i8 v[54:57], v[174:177], v[190:193], v[54:57]
	v_mfma_i32_16x16x64_i8 v[50:53], v[182:185], v[190:193], v[50:53]
	v_mfma_i32_16x16x64_i8 v[38:41], v[174:177], v[198:201], v[38:41]
	v_mfma_i32_16x16x64_i8 v[34:37], v[182:185], v[198:201], v[34:37]
	v_mfma_i32_16x16x64_i8 v[22:25], v[174:177], v[206:209], v[22:25]
	v_mfma_i32_16x16x64_i8 v[18:21], v[182:185], v[206:209], v[18:21]
	v_mfma_i32_16x16x64_i8 v[6:9], v[174:177], v[214:217], v[6:9]
	s_setprio 0
	v_mfma_i32_16x16x64_i8 v[2:5], v[182:185], v[214:217], v[2:5]
	s_barrier
	s_add_i32 s73, 0, 0x18000
	s_add_i32 s74, 0, 0x1c000
	v_add_u32_e32 v142, s73, v166
	v_add_u32_e32 v182, s74, v166
	ds_read_b128 v[130:133], v142
	ds_read_b128 v[134:137], v142 offset:1024
	ds_read_b128 v[138:141], v142 offset:2048
	ds_read_b128 v[142:145], v142 offset:3072
	ds_read_b128 v[170:173], v182
	ds_read_b128 v[174:177], v182 offset:1024
	ds_read_b128 v[178:181], v182 offset:2048
	ds_read_b128 v[182:185], v182 offset:3072
	s_add_u32 s28, s36, 0x158000
	s_addc_u32 s29, s37, 0
	s_mov_b32 m0, s49
	v_lshl_add_u64 v[224:225], s[28:29], 0, v[152:153]
	ds_read_b128 v[186:189], v169 offset:32768
	ds_read_b128 v[190:193], v169 offset:33792
	ds_read_b128 v[194:197], v169 offset:34816
	ds_read_b128 v[198:201], v169 offset:35840
	ds_read_b128 v[202:205], v169 offset:36864
	ds_read_b128 v[206:209], v169 offset:37888
	ds_read_b128 v[210:213], v169 offset:38912
	ds_read_b128 v[214:217], v169 offset:39936
	global_load_lds_dwordx4 v[224:225], off
	v_lshl_add_u64 v[224:225], s[28:29], 0, v[148:149]
	s_mov_b32 m0, s50
	s_nop 0
	global_load_lds_dwordx4 v[224:225], off
	s_setprio 1
	s_waitcnt vmcnt(8) lgkmcnt(0)
	s_barrier
	v_mfma_i32_16x16x64_i8 v[126:129], v[130:133], v[186:189], v[126:129]
	v_mfma_i32_16x16x64_i8 v[122:125], v[138:141], v[186:189], v[122:125]
	v_mfma_i32_16x16x64_i8 v[110:113], v[130:133], v[194:197], v[110:113]
	v_mfma_i32_16x16x64_i8 v[106:109], v[138:141], v[194:197], v[106:109]
	v_mfma_i32_16x16x64_i8 v[94:97], v[130:133], v[202:205], v[94:97]
	v_mfma_i32_16x16x64_i8 v[90:93], v[138:141], v[202:205], v[90:93]
	v_mfma_i32_16x16x64_i8 v[78:81], v[130:133], v[210:213], v[78:81]
	v_mfma_i32_16x16x64_i8 v[74:77], v[138:141], v[210:213], v[74:77]
	v_mfma_i32_16x16x64_i8 v[126:129], v[134:137], v[190:193], v[126:129]
	v_mfma_i32_16x16x64_i8 v[122:125], v[142:145], v[190:193], v[122:125]
	v_mfma_i32_16x16x64_i8 v[110:113], v[134:137], v[198:201], v[110:113]
	v_mfma_i32_16x16x64_i8 v[106:109], v[142:145], v[198:201], v[106:109]
	v_mfma_i32_16x16x64_i8 v[94:97], v[134:137], v[206:209], v[94:97]
	v_mfma_i32_16x16x64_i8 v[90:93], v[142:145], v[206:209], v[90:93]
	v_mfma_i32_16x16x64_i8 v[78:81], v[134:137], v[214:217], v[78:81]
	v_mfma_i32_16x16x64_i8 v[74:77], v[142:145], v[214:217], v[74:77]
	v_mfma_i32_16x16x64_i8 v[118:121], v[170:173], v[186:189], v[118:121]
	v_mfma_i32_16x16x64_i8 v[114:117], v[178:181], v[186:189], v[114:117]
	v_mfma_i32_16x16x64_i8 v[102:105], v[170:173], v[194:197], v[102:105]
	v_mfma_i32_16x16x64_i8 v[98:101], v[178:181], v[194:197], v[98:101]
	v_mfma_i32_16x16x64_i8 v[86:89], v[170:173], v[202:205], v[86:89]
	v_mfma_i32_16x16x64_i8 v[82:85], v[178:181], v[202:205], v[82:85]
	v_mfma_i32_16x16x64_i8 v[70:73], v[170:173], v[210:213], v[70:73]
	v_mfma_i32_16x16x64_i8 v[66:69], v[178:181], v[210:213], v[66:69]
	v_mfma_i32_16x16x64_i8 v[118:121], v[174:177], v[190:193], v[118:121]
	v_mfma_i32_16x16x64_i8 v[114:117], v[182:185], v[190:193], v[114:117]
	v_mfma_i32_16x16x64_i8 v[102:105], v[174:177], v[198:201], v[102:105]
	v_mfma_i32_16x16x64_i8 v[98:101], v[182:185], v[198:201], v[98:101]
	v_mfma_i32_16x16x64_i8 v[86:89], v[174:177], v[206:209], v[86:89]
	v_mfma_i32_16x16x64_i8 v[82:85], v[182:185], v[206:209], v[82:85]
	v_mfma_i32_16x16x64_i8 v[70:73], v[174:177], v[214:217], v[70:73]
	s_setprio 0
	v_mfma_i32_16x16x64_i8 v[66:69], v[182:185], v[214:217], v[66:69]
	s_barrier
	s_add_i32 s28, s73, s46
	v_lshl_add_u64 v[162:163], v[162:163], 0, s[14:15]
	s_mov_b32 m0, s28
	ds_read_b128 v[186:189], v169 offset:49152
	ds_read_b128 v[190:193], v169 offset:50176
	ds_read_b128 v[194:197], v169 offset:51200
	ds_read_b128 v[198:201], v169 offset:52224
	ds_read_b128 v[202:205], v169 offset:53248
	ds_read_b128 v[206:209], v169 offset:54272
	ds_read_b128 v[210:213], v169 offset:55296
	ds_read_b128 v[214:217], v169 offset:56320
	global_load_lds_dwordx4 v[162:163], off
	s_add_i32 m0, s28, 0x2000
	s_add_u32 s28, s34, 0x158080
	v_lshl_add_u64 v[162:163], v[218:219], 0, s[14:15]
	s_addc_u32 s29, s35, 0
	s_add_i32 s34, s74, s46
	global_load_lds_dwordx4 v[162:163], off
	v_lshl_add_u64 v[162:163], s[28:29], 0, v[150:151]
	s_mov_b32 m0, s34
	s_nop 0
	global_load_lds_dwordx4 v[162:163], off
	v_lshl_add_u64 v[162:163], s[28:29], 0, v[146:147]
	s_add_i32 m0, s34, 0x2000
	s_nop 0
	global_load_lds_dwordx4 v[162:163], off
	v_lshl_add_u64 v[162:163], v[220:221], 0, s[14:15]
	s_mov_b32 m0, s54
	s_nop 0
	global_load_lds_dwordx4 v[162:163], off
	v_lshl_add_u64 v[162:163], v[222:223], 0, s[14:15]
	s_mov_b32 m0, s55
	s_nop 0
	global_load_lds_dwordx4 v[162:163], off
	s_setprio 1
	s_waitcnt vmcnt(8) lgkmcnt(0)
	s_barrier
	v_mfma_i32_16x16x64_i8 v[62:65], v[130:133], v[186:189], v[62:65]
	v_mfma_i32_16x16x64_i8 v[58:61], v[138:141], v[186:189], v[58:61]
	v_mfma_i32_16x16x64_i8 v[46:49], v[130:133], v[194:197], v[46:49]
	v_mfma_i32_16x16x64_i8 v[42:45], v[138:141], v[194:197], v[42:45]
	v_mfma_i32_16x16x64_i8 v[30:33], v[130:133], v[202:205], v[30:33]
	v_mfma_i32_16x16x64_i8 v[26:29], v[138:141], v[202:205], v[26:29]
	v_mfma_i32_16x16x64_i8 v[14:17], v[130:133], v[210:213], v[14:17]
	v_mfma_i32_16x16x64_i8 v[10:13], v[138:141], v[210:213], v[10:13]
	v_mfma_i32_16x16x64_i8 v[62:65], v[134:137], v[190:193], v[62:65]
	v_mfma_i32_16x16x64_i8 v[58:61], v[142:145], v[190:193], v[58:61]
	v_mfma_i32_16x16x64_i8 v[46:49], v[134:137], v[198:201], v[46:49]
	v_mfma_i32_16x16x64_i8 v[42:45], v[142:145], v[198:201], v[42:45]
	v_mfma_i32_16x16x64_i8 v[30:33], v[134:137], v[206:209], v[30:33]
	v_mfma_i32_16x16x64_i8 v[26:29], v[142:145], v[206:209], v[26:29]
	v_mfma_i32_16x16x64_i8 v[14:17], v[134:137], v[214:217], v[14:17]
	v_mfma_i32_16x16x64_i8 v[10:13], v[142:145], v[214:217], v[10:13]
	v_mfma_i32_16x16x64_i8 v[54:57], v[170:173], v[186:189], v[54:57]
	v_mfma_i32_16x16x64_i8 v[50:53], v[178:181], v[186:189], v[50:53]
	v_mfma_i32_16x16x64_i8 v[38:41], v[170:173], v[194:197], v[38:41]
	v_mfma_i32_16x16x64_i8 v[34:37], v[178:181], v[194:197], v[34:37]
	v_mfma_i32_16x16x64_i8 v[22:25], v[170:173], v[202:205], v[22:25]
	v_mfma_i32_16x16x64_i8 v[18:21], v[178:181], v[202:205], v[18:21]
	v_mfma_i32_16x16x64_i8 v[6:9], v[170:173], v[210:213], v[6:9]
	v_mfma_i32_16x16x64_i8 v[2:5], v[178:181], v[210:213], v[2:5]
	v_mfma_i32_16x16x64_i8 v[54:57], v[174:177], v[190:193], v[54:57]
	v_mfma_i32_16x16x64_i8 v[50:53], v[182:185], v[190:193], v[50:53]
	v_mfma_i32_16x16x64_i8 v[38:41], v[174:177], v[198:201], v[38:41]
	v_mfma_i32_16x16x64_i8 v[34:37], v[182:185], v[198:201], v[34:37]
	v_mfma_i32_16x16x64_i8 v[22:25], v[174:177], v[206:209], v[22:25]
	v_mfma_i32_16x16x64_i8 v[18:21], v[182:185], v[206:209], v[18:21]
	v_mfma_i32_16x16x64_i8 v[6:9], v[174:177], v[214:217], v[6:9]
	s_setprio 0
	v_mfma_i32_16x16x64_i8 v[2:5], v[182:185], v[214:217], v[2:5]
	s_barrier
	s_add_i32 s72, s72, 2
	s_add_u32 s70, s70, 0x100
	s_addc_u32 s71, s71, 0
	s_cmpk_gt_u32 s72, 0x53
	s_mov_b64 s[28:29], s[30:31]
	s_cbranch_scc0 .LBB0_1099
	s_and_b64 vcc, exec, s[16:17]
	s_cbranch_vccz .LBB0_1102
	s_barrier

.LBB0_1246:
	ds_read_b128 v[130:133], v193
	ds_read_b128 v[134:137], v193 offset:1024
	ds_read_b128 v[138:141], v193 offset:2048
	ds_read_b128 v[142:145], v193 offset:3072
	ds_read_b128 v[162:165], v194
	ds_read_b128 v[166:169], v194 offset:1024
	ds_read_b128 v[170:173], v194 offset:2048
	ds_read_b128 v[174:177], v194 offset:3072
	s_add_u32 s30, s28, 0xfff00080
	s_addc_u32 s31, s29, -1
	s_cmp_eq_u32 s68, 60
	s_cselect_b32 s35, s3, s31
	s_cselect_b32 s34, s23, s30
	s_cselect_b32 s31, s17, s65
	s_cselect_b32 s30, s62, s63
	v_lshl_add_u64 v[216:217], s[28:29], 0, v[154:155]
	s_add_i32 m0, s45, 0xc000
	ds_read_b128 v[178:181], v195
	ds_read_b128 v[182:185], v195 offset:1024
	ds_read_b128 v[186:189], v195 offset:2048
	ds_read_b128 v[196:199], v195 offset:3072
	ds_read_b128 v[200:203], v195 offset:4096
	ds_read_b128 v[204:207], v195 offset:5120
	ds_read_b128 v[208:211], v195 offset:6144
	ds_read_b128 v[212:215], v195 offset:7168
	global_load_lds_dwordx4 v[216:217], off
	v_lshl_add_u64 v[216:217], s[28:29], 0, v[156:157]
	s_add_i32 m0, s45, 0xe000
	s_nop 0
	global_load_lds_dwordx4 v[216:217], off
	s_setprio 1
	s_waitcnt vmcnt(8) lgkmcnt(0)
	s_barrier
	v_mfma_f32_16x16x32_bf16 v[126:129], v[130:133], v[178:181], v[126:129]
	v_mfma_f32_16x16x32_bf16 v[122:125], v[138:141], v[178:181], v[122:125]
	v_mfma_f32_16x16x32_bf16 v[118:121], v[130:133], v[186:189], v[118:121]
	v_mfma_f32_16x16x32_bf16 v[110:113], v[138:141], v[186:189], v[110:113]
	v_mfma_f32_16x16x32_bf16 v[98:101], v[130:133], v[200:203], v[98:101]
	v_mfma_f32_16x16x32_bf16 v[90:93], v[138:141], v[200:203], v[90:93]
	v_mfma_f32_16x16x32_bf16 v[82:85], v[130:133], v[208:211], v[82:85]
	v_mfma_f32_16x16x32_bf16 v[74:77], v[138:141], v[208:211], v[74:77]
	v_mfma_f32_16x16x32_bf16 v[126:129], v[134:137], v[182:185], v[126:129]
	v_mfma_f32_16x16x32_bf16 v[122:125], v[142:145], v[182:185], v[122:125]
	v_mfma_f32_16x16x32_bf16 v[118:121], v[134:137], v[196:199], v[118:121]
	v_mfma_f32_16x16x32_bf16 v[110:113], v[142:145], v[196:199], v[110:113]
	v_mfma_f32_16x16x32_bf16 v[98:101], v[134:137], v[204:207], v[98:101]
	v_mfma_f32_16x16x32_bf16 v[90:93], v[142:145], v[204:207], v[90:93]
	v_mfma_f32_16x16x32_bf16 v[82:85], v[134:137], v[212:215], v[82:85]
	v_mfma_f32_16x16x32_bf16 v[74:77], v[142:145], v[212:215], v[74:77]
	v_mfma_f32_16x16x32_bf16 v[114:117], v[162:165], v[178:181], v[114:117]
	v_mfma_f32_16x16x32_bf16 v[106:109], v[170:173], v[178:181], v[106:109]
	v_mfma_f32_16x16x32_bf16 v[102:105], v[162:165], v[186:189], v[102:105]
	v_mfma_f32_16x16x32_bf16 v[94:97], v[170:173], v[186:189], v[94:97]
	v_mfma_f32_16x16x32_bf16 v[86:89], v[162:165], v[200:203], v[86:89]
	v_mfma_f32_16x16x32_bf16 v[78:81], v[170:173], v[200:203], v[78:81]
	v_mfma_f32_16x16x32_bf16 v[70:73], v[162:165], v[208:211], v[70:73]
	v_mfma_f32_16x16x32_bf16 v[66:69], v[170:173], v[208:211], v[66:69]
	v_mfma_f32_16x16x32_bf16 v[114:117], v[166:169], v[182:185], v[114:117]
	v_mfma_f32_16x16x32_bf16 v[106:109], v[174:177], v[182:185], v[106:109]
	v_mfma_f32_16x16x32_bf16 v[102:105], v[166:169], v[196:199], v[102:105]
	v_mfma_f32_16x16x32_bf16 v[94:97], v[174:177], v[196:199], v[94:97]
	v_mfma_f32_16x16x32_bf16 v[86:89], v[166:169], v[204:207], v[86:89]
	v_mfma_f32_16x16x32_bf16 v[78:81], v[174:177], v[204:207], v[78:81]
	v_mfma_f32_16x16x32_bf16 v[70:73], v[166:169], v[212:215], v[70:73]
	s_setprio 0
	v_mfma_f32_16x16x32_bf16 v[66:69], v[174:177], v[212:215], v[66:69]
	s_barrier
	s_add_i32 s69, s58, s44
	v_lshl_add_u64 v[216:217], s[30:31], 0, v[148:149]
	s_mov_b32 m0, s69
	ds_read_b128 v[178:181], v195 offset:16384
	ds_read_b128 v[182:185], v195 offset:17408
	ds_read_b128 v[186:189], v195 offset:18432
	ds_read_b128 v[196:199], v195 offset:19456
	ds_read_b128 v[200:203], v195 offset:20480
	ds_read_b128 v[204:207], v195 offset:21504
	ds_read_b128 v[208:211], v195 offset:22528
	ds_read_b128 v[212:215], v195 offset:23552
	global_load_lds_dwordx4 v[216:217], off
	s_add_i32 m0, s69, 0x2000
	s_add_u32 s70, s30, 0x100000
	v_lshl_add_u64 v[218:219], s[30:31], 0, v[152:153]
	s_addc_u32 s71, s31, 0
	s_add_i32 s69, s59, s44
	global_load_lds_dwordx4 v[218:219], off
	v_lshl_add_u64 v[220:221], s[70:71], 0, v[148:149]
	s_mov_b32 m0, s69
	v_lshl_add_u64 v[222:223], s[34:35], 0, v[150:151]
	global_load_lds_dwordx4 v[220:221], off
	v_lshl_add_u64 v[220:221], s[70:71], 0, v[152:153]
	s_add_i32 m0, s69, 0x2000
	s_nop 0
	global_load_lds_dwordx4 v[220:221], off
	v_lshl_add_u64 v[220:221], s[34:35], 0, v[146:147]
	s_mov_b32 m0, s45
	s_nop 0
	global_load_lds_dwordx4 v[220:221], off
	s_mov_b32 m0, s46
	s_nop 0
	global_load_lds_dwordx4 v[222:223], off
	s_setprio 1
	s_waitcnt vmcnt(8) lgkmcnt(0)
	s_barrier
	v_mfma_f32_16x16x32_bf16 v[62:65], v[130:133], v[178:181], v[62:65]
	v_mfma_f32_16x16x32_bf16 v[58:61], v[138:141], v[178:181], v[58:61]
	v_mfma_f32_16x16x32_bf16 v[46:49], v[130:133], v[186:189], v[46:49]
	v_mfma_f32_16x16x32_bf16 v[42:45], v[138:141], v[186:189], v[42:45]
	v_mfma_f32_16x16x32_bf16 v[30:33], v[130:133], v[200:203], v[30:33]
	v_mfma_f32_16x16x32_bf16 v[26:29], v[138:141], v[200:203], v[26:29]
	v_mfma_f32_16x16x32_bf16 v[14:17], v[130:133], v[208:211], v[14:17]
	v_mfma_f32_16x16x32_bf16 v[10:13], v[138:141], v[208:211], v[10:13]
	v_mfma_f32_16x16x32_bf16 v[62:65], v[134:137], v[182:185], v[62:65]
	v_mfma_f32_16x16x32_bf16 v[58:61], v[142:145], v[182:185], v[58:61]
	v_mfma_f32_16x16x32_bf16 v[46:49], v[134:137], v[196:199], v[46:49]
	v_mfma_f32_16x16x32_bf16 v[42:45], v[142:145], v[196:199], v[42:45]
	v_mfma_f32_16x16x32_bf16 v[30:33], v[134:137], v[204:207], v[30:33]
	v_mfma_f32_16x16x32_bf16 v[26:29], v[142:145], v[204:207], v[26:29]
	v_mfma_f32_16x16x32_bf16 v[14:17], v[134:137], v[212:215], v[14:17]
	v_mfma_f32_16x16x32_bf16 v[10:13], v[142:145], v[212:215], v[10:13]
	v_mfma_f32_16x16x32_bf16 v[54:57], v[162:165], v[178:181], v[54:57]
	v_mfma_f32_16x16x32_bf16 v[50:53], v[170:173], v[178:181], v[50:53]
	v_mfma_f32_16x16x32_bf16 v[38:41], v[162:165], v[186:189], v[38:41]
	v_mfma_f32_16x16x32_bf16 v[34:37], v[170:173], v[186:189], v[34:37]
	v_mfma_f32_16x16x32_bf16 v[22:25], v[162:165], v[200:203], v[22:25]
	v_mfma_f32_16x16x32_bf16 v[18:21], v[170:173], v[200:203], v[18:21]
	v_mfma_f32_16x16x32_bf16 v[6:9], v[162:165], v[208:211], v[6:9]
	v_mfma_f32_16x16x32_bf16 v[2:5], v[170:173], v[208:211], v[2:5]
	v_mfma_f32_16x16x32_bf16 v[54:57], v[166:169], v[182:185], v[54:57]
	v_mfma_f32_16x16x32_bf16 v[50:53], v[174:177], v[182:185], v[50:53]
	v_mfma_f32_16x16x32_bf16 v[38:41], v[166:169], v[196:199], v[38:41]
	v_mfma_f32_16x16x32_bf16 v[34:37], v[174:177], v[196:199], v[34:37]
	v_mfma_f32_16x16x32_bf16 v[22:25], v[166:169], v[204:207], v[22:25]
	v_mfma_f32_16x16x32_bf16 v[18:21], v[174:177], v[204:207], v[18:21]
	v_mfma_f32_16x16x32_bf16 v[6:9], v[166:169], v[212:215], v[6:9]
	s_setprio 0
	v_mfma_f32_16x16x32_bf16 v[2:5], v[174:177], v[212:215], v[2:5]
	s_barrier
	s_add_i32 s69, 0, 0x18000
	s_add_i32 s70, 0, 0x1c000
	v_add_u32_e32 v142, s69, v192
	v_add_u32_e32 v174, s70, v192
	ds_read_b128 v[130:133], v142
	ds_read_b128 v[134:137], v142 offset:1024
	ds_read_b128 v[138:141], v142 offset:2048
	ds_read_b128 v[142:145], v142 offset:3072
	ds_read_b128 v[162:165], v174
	ds_read_b128 v[166:169], v174 offset:1024
	ds_read_b128 v[170:173], v174 offset:2048
	ds_read_b128 v[174:177], v174 offset:3072
	s_add_u32 s34, s34, 0x100000
	s_addc_u32 s35, s35, 0
	s_mov_b32 m0, s47
	v_lshl_add_u64 v[224:225], s[34:35], 0, v[146:147]
	ds_read_b128 v[178:181], v195 offset:32768
	ds_read_b128 v[182:185], v195 offset:33792
	ds_read_b128 v[186:189], v195 offset:34816
	ds_read_b128 v[196:199], v195 offset:35840
	ds_read_b128 v[200:203], v195 offset:36864
	ds_read_b128 v[204:207], v195 offset:37888
	ds_read_b128 v[208:211], v195 offset:38912
	ds_read_b128 v[212:215], v195 offset:39936
	global_load_lds_dwordx4 v[224:225], off
	v_lshl_add_u64 v[224:225], s[34:35], 0, v[150:151]
	s_mov_b32 m0, s48
	s_nop 0
	global_load_lds_dwordx4 v[224:225], off
	s_setprio 1
	s_waitcnt vmcnt(8) lgkmcnt(0)
	s_barrier
	v_mfma_f32_16x16x32_bf16 v[126:129], v[130:133], v[178:181], v[126:129]
	v_mfma_f32_16x16x32_bf16 v[122:125], v[138:141], v[178:181], v[122:125]
	v_mfma_f32_16x16x32_bf16 v[118:121], v[130:133], v[186:189], v[118:121]
	v_mfma_f32_16x16x32_bf16 v[110:113], v[138:141], v[186:189], v[110:113]
	v_mfma_f32_16x16x32_bf16 v[98:101], v[130:133], v[200:203], v[98:101]
	v_mfma_f32_16x16x32_bf16 v[90:93], v[138:141], v[200:203], v[90:93]
	v_mfma_f32_16x16x32_bf16 v[82:85], v[130:133], v[208:211], v[82:85]
	v_mfma_f32_16x16x32_bf16 v[74:77], v[138:141], v[208:211], v[74:77]
	v_mfma_f32_16x16x32_bf16 v[126:129], v[134:137], v[182:185], v[126:129]
	v_mfma_f32_16x16x32_bf16 v[122:125], v[142:145], v[182:185], v[122:125]
	v_mfma_f32_16x16x32_bf16 v[118:121], v[134:137], v[196:199], v[118:121]
	v_mfma_f32_16x16x32_bf16 v[110:113], v[142:145], v[196:199], v[110:113]
	v_mfma_f32_16x16x32_bf16 v[98:101], v[134:137], v[204:207], v[98:101]
	v_mfma_f32_16x16x32_bf16 v[90:93], v[142:145], v[204:207], v[90:93]
	v_mfma_f32_16x16x32_bf16 v[82:85], v[134:137], v[212:215], v[82:85]
	v_mfma_f32_16x16x32_bf16 v[74:77], v[142:145], v[212:215], v[74:77]
	v_mfma_f32_16x16x32_bf16 v[114:117], v[162:165], v[178:181], v[114:117]
	v_mfma_f32_16x16x32_bf16 v[106:109], v[170:173], v[178:181], v[106:109]
	v_mfma_f32_16x16x32_bf16 v[102:105], v[162:165], v[186:189], v[102:105]
	v_mfma_f32_16x16x32_bf16 v[94:97], v[170:173], v[186:189], v[94:97]
	v_mfma_f32_16x16x32_bf16 v[86:89], v[162:165], v[200:203], v[86:89]
	v_mfma_f32_16x16x32_bf16 v[78:81], v[170:173], v[200:203], v[78:81]
	v_mfma_f32_16x16x32_bf16 v[70:73], v[162:165], v[208:211], v[70:73]
	v_mfma_f32_16x16x32_bf16 v[66:69], v[170:173], v[208:211], v[66:69]
	v_mfma_f32_16x16x32_bf16 v[114:117], v[166:169], v[182:185], v[114:117]
	v_mfma_f32_16x16x32_bf16 v[106:109], v[174:177], v[182:185], v[106:109]
	v_mfma_f32_16x16x32_bf16 v[102:105], v[166:169], v[196:199], v[102:105]
	v_mfma_f32_16x16x32_bf16 v[94:97], v[174:177], v[196:199], v[94:97]
	v_mfma_f32_16x16x32_bf16 v[86:89], v[166:169], v[204:207], v[86:89]
	v_mfma_f32_16x16x32_bf16 v[78:81], v[174:177], v[204:207], v[78:81]
	v_mfma_f32_16x16x32_bf16 v[70:73], v[166:169], v[212:215], v[70:73]
	s_setprio 0
	v_mfma_f32_16x16x32_bf16 v[66:69], v[174:177], v[212:215], v[66:69]
	s_barrier
	s_add_i32 s34, s69, s44
	v_lshl_add_u64 v[216:217], v[216:217], 0, s[12:13]
	s_mov_b32 m0, s34
	ds_read_b128 v[178:181], v195 offset:49152
	ds_read_b128 v[182:185], v195 offset:50176
	ds_read_b128 v[186:189], v195 offset:51200
	ds_read_b128 v[196:199], v195 offset:52224
	ds_read_b128 v[200:203], v195 offset:53248
	ds_read_b128 v[204:207], v195 offset:54272
	ds_read_b128 v[208:211], v195 offset:55296
	ds_read_b128 v[212:215], v195 offset:56320
	global_load_lds_dwordx4 v[216:217], off
	s_add_i32 m0, s34, 0x2000
	s_add_u32 s30, s30, 0x100080
	v_lshl_add_u64 v[216:217], v[218:219], 0, s[12:13]
	s_addc_u32 s31, s31, 0
	s_add_i32 s34, s70, s44
	global_load_lds_dwordx4 v[216:217], off
	v_lshl_add_u64 v[216:217], s[30:31], 0, v[148:149]
	s_mov_b32 m0, s34
	s_nop 0
	global_load_lds_dwordx4 v[216:217], off
	v_lshl_add_u64 v[216:217], s[30:31], 0, v[152:153]
	s_add_i32 m0, s34, 0x2000
	s_nop 0
	global_load_lds_dwordx4 v[216:217], off
	v_lshl_add_u64 v[216:217], v[220:221], 0, s[12:13]
	s_mov_b32 m0, s55
	s_nop 0
	global_load_lds_dwordx4 v[216:217], off
	v_lshl_add_u64 v[216:217], v[222:223], 0, s[12:13]
	s_mov_b32 m0, s56
	s_nop 0
	global_load_lds_dwordx4 v[216:217], off
	s_setprio 1
	s_waitcnt vmcnt(8) lgkmcnt(0)
	s_barrier
	v_mfma_f32_16x16x32_bf16 v[62:65], v[130:133], v[178:181], v[62:65]
	v_mfma_f32_16x16x32_bf16 v[58:61], v[138:141], v[178:181], v[58:61]
	v_mfma_f32_16x16x32_bf16 v[46:49], v[130:133], v[186:189], v[46:49]
	v_mfma_f32_16x16x32_bf16 v[42:45], v[138:141], v[186:189], v[42:45]
	v_mfma_f32_16x16x32_bf16 v[30:33], v[130:133], v[200:203], v[30:33]
	v_mfma_f32_16x16x32_bf16 v[26:29], v[138:141], v[200:203], v[26:29]
	v_mfma_f32_16x16x32_bf16 v[14:17], v[130:133], v[208:211], v[14:17]
	v_mfma_f32_16x16x32_bf16 v[10:13], v[138:141], v[208:211], v[10:13]
	v_mfma_f32_16x16x32_bf16 v[62:65], v[134:137], v[182:185], v[62:65]
	v_mfma_f32_16x16x32_bf16 v[58:61], v[142:145], v[182:185], v[58:61]
	v_mfma_f32_16x16x32_bf16 v[46:49], v[134:137], v[196:199], v[46:49]
	v_mfma_f32_16x16x32_bf16 v[42:45], v[142:145], v[196:199], v[42:45]
	v_mfma_f32_16x16x32_bf16 v[30:33], v[134:137], v[204:207], v[30:33]
	v_mfma_f32_16x16x32_bf16 v[26:29], v[142:145], v[204:207], v[26:29]
	v_mfma_f32_16x16x32_bf16 v[14:17], v[134:137], v[212:215], v[14:17]
	v_mfma_f32_16x16x32_bf16 v[10:13], v[142:145], v[212:215], v[10:13]
	v_mfma_f32_16x16x32_bf16 v[54:57], v[162:165], v[178:181], v[54:57]
	v_mfma_f32_16x16x32_bf16 v[50:53], v[170:173], v[178:181], v[50:53]
	v_mfma_f32_16x16x32_bf16 v[38:41], v[162:165], v[186:189], v[38:41]
	v_mfma_f32_16x16x32_bf16 v[34:37], v[170:173], v[186:189], v[34:37]
	v_mfma_f32_16x16x32_bf16 v[22:25], v[162:165], v[200:203], v[22:25]
	v_mfma_f32_16x16x32_bf16 v[18:21], v[170:173], v[200:203], v[18:21]
	v_mfma_f32_16x16x32_bf16 v[6:9], v[162:165], v[208:211], v[6:9]
	v_mfma_f32_16x16x32_bf16 v[2:5], v[170:173], v[208:211], v[2:5]
	v_mfma_f32_16x16x32_bf16 v[54:57], v[166:169], v[182:185], v[54:57]
	v_mfma_f32_16x16x32_bf16 v[50:53], v[174:177], v[182:185], v[50:53]
	v_mfma_f32_16x16x32_bf16 v[38:41], v[166:169], v[196:199], v[38:41]
	v_mfma_f32_16x16x32_bf16 v[34:37], v[174:177], v[196:199], v[34:37]
	v_mfma_f32_16x16x32_bf16 v[22:25], v[166:169], v[204:207], v[22:25]
	v_mfma_f32_16x16x32_bf16 v[18:21], v[174:177], v[204:207], v[18:21]
	v_mfma_f32_16x16x32_bf16 v[6:9], v[166:169], v[212:215], v[6:9]
	s_setprio 0
	v_mfma_f32_16x16x32_bf16 v[2:5], v[174:177], v[212:215], v[2:5]
	s_barrier
	s_add_i32 s68, s68, 2
	s_add_u32 s28, s28, 0x100
	s_addc_u32 s29, s29, 0
	s_add_u32 s63, s63, 0x100
	s_addc_u32 s65, s65, 0
	s_cmp_gt_u32 s68, 61
	s_cbranch_scc0 .LBB0_1246
	s_and_b64 vcc, exec, s[14:15]
	s_cbranch_vccz .LBB0_1249
	s_barrier

.LBB0_1521:
	ds_read_b128 v[130:133], v169
	ds_read_b128 v[134:137], v169 offset:1024
	ds_read_b128 v[138:141], v169 offset:2048
	ds_read_b128 v[142:145], v169 offset:3072
	ds_read_b128 v[162:165], v170
	ds_read_b128 v[172:175], v170 offset:1024
	ds_read_b128 v[176:179], v170 offset:2048
	ds_read_b128 v[180:183], v170 offset:3072
	s_add_u32 s38, s2, 0xfff00080
	s_addc_u32 s39, s3, -1
	s_cmp_eq_u32 s69, 60
	s_cselect_b32 s45, s29, s39
	s_cselect_b32 s44, s65, s38
	s_cselect_b32 s39, s27, s68
	s_cselect_b32 s38, s66, s67
	v_lshl_add_u64 v[216:217], s[2:3], 0, v[154:155]
	s_add_i32 m0, s37, 0xc000
	ds_read_b128 v[184:187], v171
	ds_read_b128 v[188:191], v171 offset:1024
	ds_read_b128 v[192:195], v171 offset:2048
	ds_read_b128 v[196:199], v171 offset:3072
	ds_read_b128 v[200:203], v171 offset:4096
	ds_read_b128 v[204:207], v171 offset:5120
	ds_read_b128 v[208:211], v171 offset:6144
	ds_read_b128 v[212:215], v171 offset:7168
	global_load_lds_dwordx4 v[216:217], off
	v_lshl_add_u64 v[216:217], s[2:3], 0, v[156:157]
	s_add_i32 m0, s37, 0xe000
	s_nop 0
	global_load_lds_dwordx4 v[216:217], off
	s_setprio 1
	s_waitcnt vmcnt(8) lgkmcnt(0)
	s_barrier
	v_mfma_f32_16x16x32_bf16 v[126:129], v[130:133], v[184:187], v[126:129]
	v_mfma_f32_16x16x32_bf16 v[122:125], v[138:141], v[184:187], v[122:125]
	v_mfma_f32_16x16x32_bf16 v[114:117], v[130:133], v[192:195], v[114:117]
	v_mfma_f32_16x16x32_bf16 v[106:109], v[138:141], v[192:195], v[106:109]
	v_mfma_f32_16x16x32_bf16 v[98:101], v[130:133], v[200:203], v[98:101]
	v_mfma_f32_16x16x32_bf16 v[90:93], v[138:141], v[200:203], v[90:93]
	v_mfma_f32_16x16x32_bf16 v[82:85], v[130:133], v[208:211], v[82:85]
	v_mfma_f32_16x16x32_bf16 v[74:77], v[138:141], v[208:211], v[74:77]
	v_mfma_f32_16x16x32_bf16 v[126:129], v[134:137], v[188:191], v[126:129]
	v_mfma_f32_16x16x32_bf16 v[122:125], v[142:145], v[188:191], v[122:125]
	v_mfma_f32_16x16x32_bf16 v[114:117], v[134:137], v[196:199], v[114:117]
	v_mfma_f32_16x16x32_bf16 v[106:109], v[142:145], v[196:199], v[106:109]
	v_mfma_f32_16x16x32_bf16 v[98:101], v[134:137], v[204:207], v[98:101]
	v_mfma_f32_16x16x32_bf16 v[90:93], v[142:145], v[204:207], v[90:93]
	v_mfma_f32_16x16x32_bf16 v[82:85], v[134:137], v[212:215], v[82:85]
	v_mfma_f32_16x16x32_bf16 v[74:77], v[142:145], v[212:215], v[74:77]
	v_mfma_f32_16x16x32_bf16 v[118:121], v[162:165], v[184:187], v[118:121]
	v_mfma_f32_16x16x32_bf16 v[110:113], v[176:179], v[184:187], v[110:113]
	v_mfma_f32_16x16x32_bf16 v[102:105], v[162:165], v[192:195], v[102:105]
	v_mfma_f32_16x16x32_bf16 v[94:97], v[176:179], v[192:195], v[94:97]
	v_mfma_f32_16x16x32_bf16 v[86:89], v[162:165], v[200:203], v[86:89]
	v_mfma_f32_16x16x32_bf16 v[78:81], v[176:179], v[200:203], v[78:81]
	v_mfma_f32_16x16x32_bf16 v[70:73], v[162:165], v[208:211], v[70:73]
	v_mfma_f32_16x16x32_bf16 v[66:69], v[176:179], v[208:211], v[66:69]
	v_mfma_f32_16x16x32_bf16 v[118:121], v[172:175], v[188:191], v[118:121]
	v_mfma_f32_16x16x32_bf16 v[110:113], v[180:183], v[188:191], v[110:113]
	v_mfma_f32_16x16x32_bf16 v[102:105], v[172:175], v[196:199], v[102:105]
	v_mfma_f32_16x16x32_bf16 v[94:97], v[180:183], v[196:199], v[94:97]
	v_mfma_f32_16x16x32_bf16 v[86:89], v[172:175], v[204:207], v[86:89]
	v_mfma_f32_16x16x32_bf16 v[78:81], v[180:183], v[204:207], v[78:81]
	v_mfma_f32_16x16x32_bf16 v[70:73], v[172:175], v[212:215], v[70:73]
	s_setprio 0
	v_mfma_f32_16x16x32_bf16 v[66:69], v[180:183], v[212:215], v[66:69]
	s_barrier
	s_add_i32 s43, s57, s50
	v_lshl_add_u64 v[216:217], s[38:39], 0, v[150:151]
	s_mov_b32 m0, s43
	ds_read_b128 v[184:187], v171 offset:16384
	ds_read_b128 v[188:191], v171 offset:17408
	ds_read_b128 v[192:195], v171 offset:18432
	ds_read_b128 v[196:199], v171 offset:19456
	ds_read_b128 v[200:203], v171 offset:20480
	ds_read_b128 v[204:207], v171 offset:21504
	ds_read_b128 v[208:211], v171 offset:22528
	ds_read_b128 v[212:215], v171 offset:23552
	global_load_lds_dwordx4 v[216:217], off
	s_add_i32 m0, s43, 0x2000
	s_add_u32 s70, s38, 0x100000
	v_lshl_add_u64 v[218:219], s[38:39], 0, v[146:147]
	s_addc_u32 s71, s39, 0
	s_add_i32 s43, s58, s50
	global_load_lds_dwordx4 v[218:219], off
	v_lshl_add_u64 v[220:221], s[70:71], 0, v[150:151]
	s_mov_b32 m0, s43
	v_lshl_add_u64 v[222:223], s[44:45], 0, v[148:149]
	global_load_lds_dwordx4 v[220:221], off
	v_lshl_add_u64 v[220:221], s[70:71], 0, v[146:147]
	s_add_i32 m0, s43, 0x2000
	s_nop 0
	global_load_lds_dwordx4 v[220:221], off
	v_lshl_add_u64 v[220:221], s[44:45], 0, v[152:153]
	s_mov_b32 m0, s37
	s_nop 0
	global_load_lds_dwordx4 v[220:221], off
	s_mov_b32 m0, s51
	s_nop 0
	global_load_lds_dwordx4 v[222:223], off
	s_setprio 1
	s_waitcnt vmcnt(8) lgkmcnt(0)
	s_barrier
	v_mfma_f32_16x16x32_bf16 v[62:65], v[130:133], v[184:187], v[62:65]
	v_mfma_f32_16x16x32_bf16 v[58:61], v[138:141], v[184:187], v[58:61]
	v_mfma_f32_16x16x32_bf16 v[50:53], v[130:133], v[192:195], v[50:53]
	v_mfma_f32_16x16x32_bf16 v[42:45], v[138:141], v[192:195], v[42:45]
	v_mfma_f32_16x16x32_bf16 v[34:37], v[130:133], v[200:203], v[34:37]
	v_mfma_f32_16x16x32_bf16 v[26:29], v[138:141], v[200:203], v[26:29]
	v_mfma_f32_16x16x32_bf16 v[18:21], v[130:133], v[208:211], v[18:21]
	v_mfma_f32_16x16x32_bf16 v[10:13], v[138:141], v[208:211], v[10:13]
	v_mfma_f32_16x16x32_bf16 v[62:65], v[134:137], v[188:191], v[62:65]
	v_mfma_f32_16x16x32_bf16 v[58:61], v[142:145], v[188:191], v[58:61]
	v_mfma_f32_16x16x32_bf16 v[50:53], v[134:137], v[196:199], v[50:53]
	v_mfma_f32_16x16x32_bf16 v[42:45], v[142:145], v[196:199], v[42:45]
	v_mfma_f32_16x16x32_bf16 v[34:37], v[134:137], v[204:207], v[34:37]
	v_mfma_f32_16x16x32_bf16 v[26:29], v[142:145], v[204:207], v[26:29]
	v_mfma_f32_16x16x32_bf16 v[18:21], v[134:137], v[212:215], v[18:21]
	v_mfma_f32_16x16x32_bf16 v[10:13], v[142:145], v[212:215], v[10:13]
	v_mfma_f32_16x16x32_bf16 v[54:57], v[162:165], v[184:187], v[54:57]
	v_mfma_f32_16x16x32_bf16 v[46:49], v[176:179], v[184:187], v[46:49]
	v_mfma_f32_16x16x32_bf16 v[38:41], v[162:165], v[192:195], v[38:41]
	v_mfma_f32_16x16x32_bf16 v[30:33], v[176:179], v[192:195], v[30:33]
	v_mfma_f32_16x16x32_bf16 v[22:25], v[162:165], v[200:203], v[22:25]
	v_mfma_f32_16x16x32_bf16 v[14:17], v[176:179], v[200:203], v[14:17]
	v_mfma_f32_16x16x32_bf16 v[6:9], v[162:165], v[208:211], v[6:9]
	v_mfma_f32_16x16x32_bf16 v[2:5], v[176:179], v[208:211], v[2:5]
	v_mfma_f32_16x16x32_bf16 v[54:57], v[172:175], v[188:191], v[54:57]
	v_mfma_f32_16x16x32_bf16 v[46:49], v[180:183], v[188:191], v[46:49]
	v_mfma_f32_16x16x32_bf16 v[38:41], v[172:175], v[196:199], v[38:41]
	v_mfma_f32_16x16x32_bf16 v[30:33], v[180:183], v[196:199], v[30:33]
	v_mfma_f32_16x16x32_bf16 v[22:25], v[172:175], v[204:207], v[22:25]
	v_mfma_f32_16x16x32_bf16 v[14:17], v[180:183], v[204:207], v[14:17]
	v_mfma_f32_16x16x32_bf16 v[6:9], v[172:175], v[212:215], v[6:9]
	s_setprio 0
	v_mfma_f32_16x16x32_bf16 v[2:5], v[180:183], v[212:215], v[2:5]
	s_barrier
	s_add_i32 s43, 0, 0x18000
	s_add_i32 s70, 0, 0x1c000
	v_add_u32_e32 v142, s43, v167
	v_add_u32_e32 v180, s70, v167
	ds_read_b128 v[130:133], v142
	ds_read_b128 v[134:137], v142 offset:1024
	ds_read_b128 v[138:141], v142 offset:2048
	ds_read_b128 v[142:145], v142 offset:3072
	ds_read_b128 v[162:165], v180
	ds_read_b128 v[172:175], v180 offset:1024
	ds_read_b128 v[176:179], v180 offset:2048
	ds_read_b128 v[180:183], v180 offset:3072
	s_add_u32 s44, s44, 0x100000
	s_addc_u32 s45, s45, 0
	s_mov_b32 m0, s52
	v_lshl_add_u64 v[224:225], s[44:45], 0, v[152:153]
	ds_read_b128 v[184:187], v171 offset:32768
	ds_read_b128 v[188:191], v171 offset:33792
	ds_read_b128 v[192:195], v171 offset:34816
	ds_read_b128 v[196:199], v171 offset:35840
	ds_read_b128 v[200:203], v171 offset:36864
	ds_read_b128 v[204:207], v171 offset:37888
	ds_read_b128 v[208:211], v171 offset:38912
	ds_read_b128 v[212:215], v171 offset:39936
	global_load_lds_dwordx4 v[224:225], off
	v_lshl_add_u64 v[224:225], s[44:45], 0, v[148:149]
	s_mov_b32 m0, s53
	s_nop 0
	global_load_lds_dwordx4 v[224:225], off
	s_setprio 1
	s_waitcnt vmcnt(8) lgkmcnt(0)
	s_barrier
	v_mfma_f32_16x16x32_bf16 v[126:129], v[130:133], v[184:187], v[126:129]
	v_mfma_f32_16x16x32_bf16 v[122:125], v[138:141], v[184:187], v[122:125]
	v_mfma_f32_16x16x32_bf16 v[114:117], v[130:133], v[192:195], v[114:117]
	v_mfma_f32_16x16x32_bf16 v[106:109], v[138:141], v[192:195], v[106:109]
	v_mfma_f32_16x16x32_bf16 v[98:101], v[130:133], v[200:203], v[98:101]
	v_mfma_f32_16x16x32_bf16 v[90:93], v[138:141], v[200:203], v[90:93]
	v_mfma_f32_16x16x32_bf16 v[82:85], v[130:133], v[208:211], v[82:85]
	v_mfma_f32_16x16x32_bf16 v[74:77], v[138:141], v[208:211], v[74:77]
	v_mfma_f32_16x16x32_bf16 v[126:129], v[134:137], v[188:191], v[126:129]
	v_mfma_f32_16x16x32_bf16 v[122:125], v[142:145], v[188:191], v[122:125]
	v_mfma_f32_16x16x32_bf16 v[114:117], v[134:137], v[196:199], v[114:117]
	v_mfma_f32_16x16x32_bf16 v[106:109], v[142:145], v[196:199], v[106:109]
	v_mfma_f32_16x16x32_bf16 v[98:101], v[134:137], v[204:207], v[98:101]
	v_mfma_f32_16x16x32_bf16 v[90:93], v[142:145], v[204:207], v[90:93]
	v_mfma_f32_16x16x32_bf16 v[82:85], v[134:137], v[212:215], v[82:85]
	v_mfma_f32_16x16x32_bf16 v[74:77], v[142:145], v[212:215], v[74:77]
	v_mfma_f32_16x16x32_bf16 v[118:121], v[162:165], v[184:187], v[118:121]
	v_mfma_f32_16x16x32_bf16 v[110:113], v[176:179], v[184:187], v[110:113]
	v_mfma_f32_16x16x32_bf16 v[102:105], v[162:165], v[192:195], v[102:105]
	v_mfma_f32_16x16x32_bf16 v[94:97], v[176:179], v[192:195], v[94:97]
	v_mfma_f32_16x16x32_bf16 v[86:89], v[162:165], v[200:203], v[86:89]
	v_mfma_f32_16x16x32_bf16 v[78:81], v[176:179], v[200:203], v[78:81]
	v_mfma_f32_16x16x32_bf16 v[70:73], v[162:165], v[208:211], v[70:73]
	v_mfma_f32_16x16x32_bf16 v[66:69], v[176:179], v[208:211], v[66:69]
	v_mfma_f32_16x16x32_bf16 v[118:121], v[172:175], v[188:191], v[118:121]
	v_mfma_f32_16x16x32_bf16 v[110:113], v[180:183], v[188:191], v[110:113]
	v_mfma_f32_16x16x32_bf16 v[102:105], v[172:175], v[196:199], v[102:105]
	v_mfma_f32_16x16x32_bf16 v[94:97], v[180:183], v[196:199], v[94:97]
	v_mfma_f32_16x16x32_bf16 v[86:89], v[172:175], v[204:207], v[86:89]
	v_mfma_f32_16x16x32_bf16 v[78:81], v[180:183], v[204:207], v[78:81]
	v_mfma_f32_16x16x32_bf16 v[70:73], v[172:175], v[212:215], v[70:73]
	s_setprio 0
	v_mfma_f32_16x16x32_bf16 v[66:69], v[180:183], v[212:215], v[66:69]
	s_barrier
	s_add_i32 s43, s43, s50
	v_lshl_add_u64 v[216:217], v[216:217], 0, s[16:17]
	s_mov_b32 m0, s43
	ds_read_b128 v[184:187], v171 offset:49152
	ds_read_b128 v[188:191], v171 offset:50176
	ds_read_b128 v[192:195], v171 offset:51200
	ds_read_b128 v[196:199], v171 offset:52224
	ds_read_b128 v[200:203], v171 offset:53248
	ds_read_b128 v[204:207], v171 offset:54272
	ds_read_b128 v[208:211], v171 offset:55296
	ds_read_b128 v[212:215], v171 offset:56320
	global_load_lds_dwordx4 v[216:217], off
	s_add_i32 m0, s43, 0x2000
	s_add_u32 s38, s38, 0x100080
	v_lshl_add_u64 v[216:217], v[218:219], 0, s[16:17]
	s_addc_u32 s39, s39, 0
	s_add_i32 s43, s70, s50
	global_load_lds_dwordx4 v[216:217], off
	v_lshl_add_u64 v[216:217], s[38:39], 0, v[150:151]
	s_mov_b32 m0, s43
	s_nop 0
	global_load_lds_dwordx4 v[216:217], off
	v_lshl_add_u64 v[216:217], s[38:39], 0, v[146:147]
	s_add_i32 m0, s43, 0x2000
	s_nop 0
	global_load_lds_dwordx4 v[216:217], off
	v_lshl_add_u64 v[216:217], v[220:221], 0, s[16:17]
	s_mov_b32 m0, s55
	s_nop 0
	global_load_lds_dwordx4 v[216:217], off
	v_lshl_add_u64 v[216:217], v[222:223], 0, s[16:17]
	s_mov_b32 m0, s56
	s_nop 0
	global_load_lds_dwordx4 v[216:217], off
	s_setprio 1
	s_waitcnt vmcnt(8) lgkmcnt(0)
	s_barrier
	v_mfma_f32_16x16x32_bf16 v[62:65], v[130:133], v[184:187], v[62:65]
	v_mfma_f32_16x16x32_bf16 v[58:61], v[138:141], v[184:187], v[58:61]
	v_mfma_f32_16x16x32_bf16 v[50:53], v[130:133], v[192:195], v[50:53]
	v_mfma_f32_16x16x32_bf16 v[42:45], v[138:141], v[192:195], v[42:45]
	v_mfma_f32_16x16x32_bf16 v[34:37], v[130:133], v[200:203], v[34:37]
	v_mfma_f32_16x16x32_bf16 v[26:29], v[138:141], v[200:203], v[26:29]
	v_mfma_f32_16x16x32_bf16 v[18:21], v[130:133], v[208:211], v[18:21]
	v_mfma_f32_16x16x32_bf16 v[10:13], v[138:141], v[208:211], v[10:13]
	v_mfma_f32_16x16x32_bf16 v[62:65], v[134:137], v[188:191], v[62:65]
	v_mfma_f32_16x16x32_bf16 v[58:61], v[142:145], v[188:191], v[58:61]
	v_mfma_f32_16x16x32_bf16 v[50:53], v[134:137], v[196:199], v[50:53]
	v_mfma_f32_16x16x32_bf16 v[42:45], v[142:145], v[196:199], v[42:45]
	v_mfma_f32_16x16x32_bf16 v[34:37], v[134:137], v[204:207], v[34:37]
	v_mfma_f32_16x16x32_bf16 v[26:29], v[142:145], v[204:207], v[26:29]
	v_mfma_f32_16x16x32_bf16 v[18:21], v[134:137], v[212:215], v[18:21]
	v_mfma_f32_16x16x32_bf16 v[10:13], v[142:145], v[212:215], v[10:13]
	v_mfma_f32_16x16x32_bf16 v[54:57], v[162:165], v[184:187], v[54:57]
	v_mfma_f32_16x16x32_bf16 v[46:49], v[176:179], v[184:187], v[46:49]
	v_mfma_f32_16x16x32_bf16 v[38:41], v[162:165], v[192:195], v[38:41]
	v_mfma_f32_16x16x32_bf16 v[30:33], v[176:179], v[192:195], v[30:33]
	v_mfma_f32_16x16x32_bf16 v[22:25], v[162:165], v[200:203], v[22:25]
	v_mfma_f32_16x16x32_bf16 v[14:17], v[176:179], v[200:203], v[14:17]
	v_mfma_f32_16x16x32_bf16 v[6:9], v[162:165], v[208:211], v[6:9]
	v_mfma_f32_16x16x32_bf16 v[2:5], v[176:179], v[208:211], v[2:5]
	v_mfma_f32_16x16x32_bf16 v[54:57], v[172:175], v[188:191], v[54:57]
	v_mfma_f32_16x16x32_bf16 v[46:49], v[180:183], v[188:191], v[46:49]
	v_mfma_f32_16x16x32_bf16 v[38:41], v[172:175], v[196:199], v[38:41]
	v_mfma_f32_16x16x32_bf16 v[30:33], v[180:183], v[196:199], v[30:33]
	v_mfma_f32_16x16x32_bf16 v[22:25], v[172:175], v[204:207], v[22:25]
	v_mfma_f32_16x16x32_bf16 v[14:17], v[180:183], v[204:207], v[14:17]
	v_mfma_f32_16x16x32_bf16 v[6:9], v[172:175], v[212:215], v[6:9]
	s_setprio 0
	v_mfma_f32_16x16x32_bf16 v[2:5], v[180:183], v[212:215], v[2:5]
	s_barrier
	s_add_i32 s69, s69, 2
	s_add_u32 s2, s2, 0x100
	s_addc_u32 s3, s3, 0
	s_add_u32 s67, s67, 0x100
	s_addc_u32 s68, s68, 0
	s_cmp_gt_u32 s69, 61
	s_cbranch_scc0 .LBB0_1521
	s_and_b64 vcc, exec, s[18:19]
	s_cbranch_vccz .LBB0_1524
	s_barrier

.LBB0_1697:
	ds_read_b128 v[130:133], v238
	ds_read_b128 v[134:137], v238 offset:1024
	ds_read_b128 v[138:141], v238 offset:2048
	ds_read_b128 v[142:145], v238 offset:3072
	ds_read_b128 v[146:149], v239
	ds_read_b128 v[150:153], v239 offset:1024
	ds_read_b128 v[154:157], v239 offset:2048
	ds_read_b128 v[158:161], v239 offset:3072
	s_add_u32 s56, s2, 0x100
	s_addc_u32 s57, s3, 0
	s_cmp_eq_u32 s91, 28
	s_cselect_b32 s61, s49, s57
	s_cselect_b32 s60, s87, s56
	s_cselect_b32 s59, s47, s90
	s_cselect_b32 s58, s88, s89
	v_lshl_add_u64 v[194:195], s[2:3], 0, v[210:211]
	s_add_i32 m0, s55, 0xc000
	ds_read_b128 v[162:165], v240
	ds_read_b128 v[166:169], v240 offset:1024
	ds_read_b128 v[170:173], v240 offset:2048
	ds_read_b128 v[174:177], v240 offset:3072
	ds_read_b128 v[178:181], v240 offset:4096
	ds_read_b128 v[182:185], v240 offset:5120
	ds_read_b128 v[186:189], v240 offset:6144
	ds_read_b128 v[190:193], v240 offset:7168
	global_load_lds_dwordx4 v[194:195], off
	v_lshl_add_u64 v[194:195], s[2:3], 0, v[212:213]
	s_add_i32 m0, s55, 0xe000
	s_nop 0
	global_load_lds_dwordx4 v[194:195], off
	s_setprio 1
	s_waitcnt vmcnt(8) lgkmcnt(0)
	s_barrier
	v_mfma_i32_16x16x64_i8 v[126:129], v[130:133], v[162:165], v[126:129]
	v_mfma_i32_16x16x64_i8 v[122:125], v[138:141], v[162:165], v[122:125]
	v_mfma_i32_16x16x64_i8 v[118:121], v[130:133], v[170:173], v[118:121]
	v_mfma_i32_16x16x64_i8 v[110:113], v[138:141], v[170:173], v[110:113]
	v_mfma_i32_16x16x64_i8 v[78:81], v[130:133], v[178:181], v[78:81]
	v_mfma_i32_16x16x64_i8 v[30:33], v[138:141], v[178:181], v[30:33]
	v_mfma_i32_16x16x64_i8 v[74:77], v[130:133], v[186:189], v[74:77]
	v_mfma_i32_16x16x64_i8 v[26:29], v[138:141], v[186:189], v[26:29]
	v_mfma_i32_16x16x64_i8 v[126:129], v[134:137], v[166:169], v[126:129]
	v_mfma_i32_16x16x64_i8 v[122:125], v[142:145], v[166:169], v[122:125]
	v_mfma_i32_16x16x64_i8 v[118:121], v[134:137], v[174:177], v[118:121]
	v_mfma_i32_16x16x64_i8 v[110:113], v[142:145], v[174:177], v[110:113]
	v_mfma_i32_16x16x64_i8 v[78:81], v[134:137], v[182:185], v[78:81]
	v_mfma_i32_16x16x64_i8 v[30:33], v[142:145], v[182:185], v[30:33]
	v_mfma_i32_16x16x64_i8 v[74:77], v[134:137], v[190:193], v[74:77]
	v_mfma_i32_16x16x64_i8 v[26:29], v[142:145], v[190:193], v[26:29]
	v_mfma_i32_16x16x64_i8 v[102:105], v[146:149], v[162:165], v[102:105]
	v_mfma_i32_16x16x64_i8 v[98:101], v[154:157], v[162:165], v[98:101]
	v_mfma_i32_16x16x64_i8 v[94:97], v[146:149], v[170:173], v[94:97]
	v_mfma_i32_16x16x64_i8 v[90:93], v[154:157], v[170:173], v[90:93]
	v_mfma_i32_16x16x64_i8 v[70:73], v[146:149], v[178:181], v[70:73]
	v_mfma_i32_16x16x64_i8 v[22:25], v[154:157], v[178:181], v[22:25]
	v_mfma_i32_16x16x64_i8 v[66:69], v[146:149], v[186:189], v[66:69]
	v_mfma_i32_16x16x64_i8 v[18:21], v[154:157], v[186:189], v[18:21]
	v_mfma_i32_16x16x64_i8 v[102:105], v[150:153], v[166:169], v[102:105]
	v_mfma_i32_16x16x64_i8 v[98:101], v[158:161], v[166:169], v[98:101]
	v_mfma_i32_16x16x64_i8 v[94:97], v[150:153], v[174:177], v[94:97]
	v_mfma_i32_16x16x64_i8 v[90:93], v[158:161], v[174:177], v[90:93]
	v_mfma_i32_16x16x64_i8 v[70:73], v[150:153], v[182:185], v[70:73]
	v_mfma_i32_16x16x64_i8 v[22:25], v[158:161], v[182:185], v[22:25]
	v_mfma_i32_16x16x64_i8 v[66:69], v[150:153], v[190:193], v[66:69]
	s_setprio 0
	v_mfma_i32_16x16x64_i8 v[18:21], v[158:161], v[190:193], v[18:21]
	s_barrier
	s_add_i32 s2, s83, s66
	v_lshl_add_u64 v[194:195], s[58:59], 0, v[206:207]
	s_mov_b32 m0, s2
	ds_read_b128 v[162:165], v240 offset:16384
	ds_read_b128 v[166:169], v240 offset:17408
	ds_read_b128 v[170:173], v240 offset:18432
	ds_read_b128 v[174:177], v240 offset:19456
	ds_read_b128 v[178:181], v240 offset:20480
	ds_read_b128 v[182:185], v240 offset:21504
	ds_read_b128 v[186:189], v240 offset:22528
	ds_read_b128 v[190:193], v240 offset:23552
	global_load_lds_dwordx4 v[194:195], off
	s_add_i32 m0, s2, 0x2000
	s_add_u32 s2, s58, 0x80000
	v_lshl_add_u64 v[196:197], s[58:59], 0, v[202:203]
	s_addc_u32 s3, s59, 0
	s_add_i32 s43, s84, s66
	global_load_lds_dwordx4 v[196:197], off
	v_lshl_add_u64 v[198:199], s[2:3], 0, v[206:207]
	s_mov_b32 m0, s43
	v_lshl_add_u64 v[200:201], s[60:61], 0, v[204:205]
	global_load_lds_dwordx4 v[198:199], off
	v_lshl_add_u64 v[198:199], s[2:3], 0, v[202:203]
	s_add_i32 m0, s43, 0x2000
	s_nop 0
	global_load_lds_dwordx4 v[198:199], off
	v_lshl_add_u64 v[198:199], s[60:61], 0, v[208:209]
	s_mov_b32 m0, s55
	s_nop 0
	global_load_lds_dwordx4 v[198:199], off
	s_mov_b32 m0, s68
	s_nop 0
	global_load_lds_dwordx4 v[200:201], off
	s_setprio 1
	s_waitcnt vmcnt(8) lgkmcnt(0)
	s_barrier
	v_mfma_i32_16x16x64_i8 v[62:65], v[130:133], v[162:165], v[62:65]
	v_mfma_i32_16x16x64_i8 v[14:17], v[138:141], v[162:165], v[14:17]
	v_mfma_i32_16x16x64_i8 v[58:61], v[130:133], v[170:173], v[58:61]
	v_mfma_i32_16x16x64_i8 v[10:13], v[138:141], v[170:173], v[10:13]
	v_mfma_i32_16x16x64_i8 v[114:117], v[130:133], v[178:181], v[114:117]
	v_mfma_i32_16x16x64_i8 v[106:109], v[138:141], v[178:181], v[106:109]
	v_mfma_i32_16x16x64_i8 v[86:89], v[130:133], v[186:189], v[86:89]
	v_mfma_i32_16x16x64_i8 v[82:85], v[138:141], v[186:189], v[82:85]
	v_mfma_i32_16x16x64_i8 v[62:65], v[134:137], v[166:169], v[62:65]
	v_mfma_i32_16x16x64_i8 v[14:17], v[142:145], v[166:169], v[14:17]
	v_mfma_i32_16x16x64_i8 v[58:61], v[134:137], v[174:177], v[58:61]
	v_mfma_i32_16x16x64_i8 v[10:13], v[142:145], v[174:177], v[10:13]
	v_mfma_i32_16x16x64_i8 v[114:117], v[134:137], v[182:185], v[114:117]
	v_mfma_i32_16x16x64_i8 v[106:109], v[142:145], v[182:185], v[106:109]
	v_mfma_i32_16x16x64_i8 v[86:89], v[134:137], v[190:193], v[86:89]
	v_mfma_i32_16x16x64_i8 v[82:85], v[142:145], v[190:193], v[82:85]
	v_mfma_i32_16x16x64_i8 v[50:53], v[146:149], v[162:165], v[50:53]
	v_mfma_i32_16x16x64_i8 v[6:9], v[154:157], v[162:165], v[6:9]
	v_mfma_i32_16x16x64_i8 v[42:45], v[146:149], v[170:173], v[42:45]
	v_mfma_i32_16x16x64_i8 v[2:5], v[154:157], v[170:173], v[2:5]
	v_mfma_i32_16x16x64_i8 v[54:57], v[146:149], v[178:181], v[54:57]
	v_mfma_i32_16x16x64_i8 v[46:49], v[154:157], v[178:181], v[46:49]
	v_mfma_i32_16x16x64_i8 v[38:41], v[146:149], v[186:189], v[38:41]
	v_mfma_i32_16x16x64_i8 v[34:37], v[154:157], v[186:189], v[34:37]
	v_mfma_i32_16x16x64_i8 v[50:53], v[150:153], v[166:169], v[50:53]
	v_mfma_i32_16x16x64_i8 v[6:9], v[158:161], v[166:169], v[6:9]
	v_mfma_i32_16x16x64_i8 v[42:45], v[150:153], v[174:177], v[42:45]
	v_mfma_i32_16x16x64_i8 v[2:5], v[158:161], v[174:177], v[2:5]
	v_mfma_i32_16x16x64_i8 v[54:57], v[150:153], v[182:185], v[54:57]
	v_mfma_i32_16x16x64_i8 v[46:49], v[158:161], v[182:185], v[46:49]
	v_mfma_i32_16x16x64_i8 v[38:41], v[150:153], v[190:193], v[38:41]
	s_setprio 0
	v_mfma_i32_16x16x64_i8 v[34:37], v[158:161], v[190:193], v[34:37]
	s_barrier
	s_add_i32 s43, 0, 0x18000
	s_add_i32 s92, 0, 0x1c000
	v_add_u32_e32 v142, s43, v237
	v_add_u32_e32 v158, s92, v237
	ds_read_b128 v[130:133], v142
	ds_read_b128 v[134:137], v142 offset:1024
	ds_read_b128 v[138:141], v142 offset:2048
	ds_read_b128 v[142:145], v142 offset:3072
	ds_read_b128 v[146:149], v158
	ds_read_b128 v[150:153], v158 offset:1024
	ds_read_b128 v[154:157], v158 offset:2048
	ds_read_b128 v[158:161], v158 offset:3072
	s_add_u32 s2, s60, 0x4000
	s_addc_u32 s3, s61, 0
	s_mov_b32 m0, s69
	v_lshl_add_u64 v[220:221], s[2:3], 0, v[208:209]
	ds_read_b128 v[162:165], v240 offset:32768
	ds_read_b128 v[166:169], v240 offset:33792
	ds_read_b128 v[170:173], v240 offset:34816
	ds_read_b128 v[174:177], v240 offset:35840
	ds_read_b128 v[178:181], v240 offset:36864
	ds_read_b128 v[182:185], v240 offset:37888
	ds_read_b128 v[186:189], v240 offset:38912
	ds_read_b128 v[190:193], v240 offset:39936
	global_load_lds_dwordx4 v[220:221], off
	v_lshl_add_u64 v[220:221], s[2:3], 0, v[204:205]
	s_mov_b32 m0, s70
	s_nop 0
	global_load_lds_dwordx4 v[220:221], off
	s_setprio 1
	s_waitcnt vmcnt(8) lgkmcnt(0)
	s_barrier
	v_mfma_i32_16x16x64_i8 v[126:129], v[130:133], v[162:165], v[126:129]
	v_mfma_i32_16x16x64_i8 v[122:125], v[138:141], v[162:165], v[122:125]
	v_mfma_i32_16x16x64_i8 v[118:121], v[130:133], v[170:173], v[118:121]
	v_mfma_i32_16x16x64_i8 v[110:113], v[138:141], v[170:173], v[110:113]
	v_mfma_i32_16x16x64_i8 v[78:81], v[130:133], v[178:181], v[78:81]
	v_mfma_i32_16x16x64_i8 v[30:33], v[138:141], v[178:181], v[30:33]
	v_mfma_i32_16x16x64_i8 v[74:77], v[130:133], v[186:189], v[74:77]
	v_mfma_i32_16x16x64_i8 v[26:29], v[138:141], v[186:189], v[26:29]
	v_mfma_i32_16x16x64_i8 v[126:129], v[134:137], v[166:169], v[126:129]
	v_mfma_i32_16x16x64_i8 v[122:125], v[142:145], v[166:169], v[122:125]
	v_mfma_i32_16x16x64_i8 v[118:121], v[134:137], v[174:177], v[118:121]
	v_mfma_i32_16x16x64_i8 v[110:113], v[142:145], v[174:177], v[110:113]
	v_mfma_i32_16x16x64_i8 v[78:81], v[134:137], v[182:185], v[78:81]
	v_mfma_i32_16x16x64_i8 v[30:33], v[142:145], v[182:185], v[30:33]
	v_mfma_i32_16x16x64_i8 v[74:77], v[134:137], v[190:193], v[74:77]
	v_mfma_i32_16x16x64_i8 v[26:29], v[142:145], v[190:193], v[26:29]
	v_mfma_i32_16x16x64_i8 v[102:105], v[146:149], v[162:165], v[102:105]
	v_mfma_i32_16x16x64_i8 v[98:101], v[154:157], v[162:165], v[98:101]
	v_mfma_i32_16x16x64_i8 v[94:97], v[146:149], v[170:173], v[94:97]
	v_mfma_i32_16x16x64_i8 v[90:93], v[154:157], v[170:173], v[90:93]
	v_mfma_i32_16x16x64_i8 v[70:73], v[146:149], v[178:181], v[70:73]
	v_mfma_i32_16x16x64_i8 v[22:25], v[154:157], v[178:181], v[22:25]
	v_mfma_i32_16x16x64_i8 v[66:69], v[146:149], v[186:189], v[66:69]
	v_mfma_i32_16x16x64_i8 v[18:21], v[154:157], v[186:189], v[18:21]
	v_mfma_i32_16x16x64_i8 v[102:105], v[150:153], v[166:169], v[102:105]
	v_mfma_i32_16x16x64_i8 v[98:101], v[158:161], v[166:169], v[98:101]
	v_mfma_i32_16x16x64_i8 v[94:97], v[150:153], v[174:177], v[94:97]
	v_mfma_i32_16x16x64_i8 v[90:93], v[158:161], v[174:177], v[90:93]
	v_mfma_i32_16x16x64_i8 v[70:73], v[150:153], v[182:185], v[70:73]
	v_mfma_i32_16x16x64_i8 v[22:25], v[158:161], v[182:185], v[22:25]
	v_mfma_i32_16x16x64_i8 v[66:69], v[150:153], v[190:193], v[66:69]
	s_setprio 0
	v_mfma_i32_16x16x64_i8 v[18:21], v[158:161], v[190:193], v[18:21]
	s_barrier
	s_add_i32 s2, s43, s66
	v_lshl_add_u64 v[194:195], v[194:195], 0, s[36:37]
	s_mov_b32 m0, s2
	ds_read_b128 v[162:165], v240 offset:49152
	ds_read_b128 v[166:169], v240 offset:50176
	ds_read_b128 v[170:173], v240 offset:51200
	ds_read_b128 v[174:177], v240 offset:52224
	ds_read_b128 v[178:181], v240 offset:53248
	ds_read_b128 v[182:185], v240 offset:54272
	ds_read_b128 v[186:189], v240 offset:55296
	ds_read_b128 v[190:193], v240 offset:56320
	global_load_lds_dwordx4 v[194:195], off
	s_add_i32 m0, s2, 0x2000
	s_add_u32 s2, s58, 0x80080
	v_lshl_add_u64 v[194:195], v[196:197], 0, s[36:37]
	s_addc_u32 s3, s59, 0
	s_add_i32 s43, s92, s66
	global_load_lds_dwordx4 v[194:195], off
	v_lshl_add_u64 v[194:195], s[2:3], 0, v[206:207]
	s_mov_b32 m0, s43
	s_nop 0
	global_load_lds_dwordx4 v[194:195], off
	v_lshl_add_u64 v[194:195], s[2:3], 0, v[202:203]
	s_add_i32 m0, s43, 0x2000
	s_nop 0
	global_load_lds_dwordx4 v[194:195], off
	v_lshl_add_u64 v[194:195], v[198:199], 0, s[36:37]
	s_mov_b32 m0, s77
	s_nop 0
	global_load_lds_dwordx4 v[194:195], off
	v_lshl_add_u64 v[194:195], v[200:201], 0, s[36:37]
	s_mov_b32 m0, s78
	s_nop 0
	global_load_lds_dwordx4 v[194:195], off
	s_setprio 1
	s_waitcnt vmcnt(8) lgkmcnt(0)
	s_barrier
	v_mfma_i32_16x16x64_i8 v[62:65], v[130:133], v[162:165], v[62:65]
	v_mfma_i32_16x16x64_i8 v[14:17], v[138:141], v[162:165], v[14:17]
	v_mfma_i32_16x16x64_i8 v[58:61], v[130:133], v[170:173], v[58:61]
	v_mfma_i32_16x16x64_i8 v[10:13], v[138:141], v[170:173], v[10:13]
	v_mfma_i32_16x16x64_i8 v[114:117], v[130:133], v[178:181], v[114:117]
	v_mfma_i32_16x16x64_i8 v[106:109], v[138:141], v[178:181], v[106:109]
	v_mfma_i32_16x16x64_i8 v[86:89], v[130:133], v[186:189], v[86:89]
	v_mfma_i32_16x16x64_i8 v[82:85], v[138:141], v[186:189], v[82:85]
	v_mfma_i32_16x16x64_i8 v[62:65], v[134:137], v[166:169], v[62:65]
	v_mfma_i32_16x16x64_i8 v[14:17], v[142:145], v[166:169], v[14:17]
	v_mfma_i32_16x16x64_i8 v[58:61], v[134:137], v[174:177], v[58:61]
	v_mfma_i32_16x16x64_i8 v[10:13], v[142:145], v[174:177], v[10:13]
	v_mfma_i32_16x16x64_i8 v[114:117], v[134:137], v[182:185], v[114:117]
	v_mfma_i32_16x16x64_i8 v[106:109], v[142:145], v[182:185], v[106:109]
	v_mfma_i32_16x16x64_i8 v[86:89], v[134:137], v[190:193], v[86:89]
	v_mfma_i32_16x16x64_i8 v[82:85], v[142:145], v[190:193], v[82:85]
	v_mfma_i32_16x16x64_i8 v[50:53], v[146:149], v[162:165], v[50:53]
	v_mfma_i32_16x16x64_i8 v[6:9], v[154:157], v[162:165], v[6:9]
	v_mfma_i32_16x16x64_i8 v[42:45], v[146:149], v[170:173], v[42:45]
	v_mfma_i32_16x16x64_i8 v[2:5], v[154:157], v[170:173], v[2:5]
	v_mfma_i32_16x16x64_i8 v[54:57], v[146:149], v[178:181], v[54:57]
	v_mfma_i32_16x16x64_i8 v[46:49], v[154:157], v[178:181], v[46:49]
	v_mfma_i32_16x16x64_i8 v[38:41], v[146:149], v[186:189], v[38:41]
	v_mfma_i32_16x16x64_i8 v[34:37], v[154:157], v[186:189], v[34:37]
	v_mfma_i32_16x16x64_i8 v[50:53], v[150:153], v[166:169], v[50:53]
	v_mfma_i32_16x16x64_i8 v[6:9], v[158:161], v[166:169], v[6:9]
	v_mfma_i32_16x16x64_i8 v[42:45], v[150:153], v[174:177], v[42:45]
	v_mfma_i32_16x16x64_i8 v[2:5], v[158:161], v[174:177], v[2:5]
	v_mfma_i32_16x16x64_i8 v[54:57], v[150:153], v[182:185], v[54:57]
	v_mfma_i32_16x16x64_i8 v[46:49], v[158:161], v[182:185], v[46:49]
	v_mfma_i32_16x16x64_i8 v[38:41], v[150:153], v[190:193], v[38:41]
	s_setprio 0
	v_mfma_i32_16x16x64_i8 v[34:37], v[158:161], v[190:193], v[34:37]
	s_barrier
	s_add_i32 s91, s91, 2
	s_add_u32 s89, s89, 0x100
	s_addc_u32 s90, s90, 0
	s_cmp_gt_u32 s91, 29
	s_mov_b64 s[2:3], s[56:57]
	s_cbranch_scc0 .LBB0_1697
	s_and_b64 vcc, exec, s[38:39]
	s_cbranch_vccz .LBB0_1700
	s_barrier

.LBB0_1951:
	ds_read_b128 v[130:133], v167
	ds_read_b128 v[134:137], v167 offset:1024
	ds_read_b128 v[138:141], v167 offset:2048
	ds_read_b128 v[142:145], v167 offset:3072
	ds_read_b128 v[170:173], v168
	ds_read_b128 v[174:177], v168 offset:1024
	ds_read_b128 v[178:181], v168 offset:2048
	ds_read_b128 v[182:185], v168 offset:3072
	s_add_u32 s38, s36, 0x100
	s_addc_u32 s39, s37, 0
	s_cmpk_eq_i32 s77, 0x52
	s_cselect_b32 s47, s3, s39
	s_cselect_b32 s46, s2, s38
	s_cselect_b32 s45, s35, s76
	s_cselect_b32 s44, s34, s75
	v_lshl_add_u64 v[162:163], s[36:37], 0, v[154:155]
	s_add_i32 m0, s52, 0xc000
	ds_read_b128 v[186:189], v169
	ds_read_b128 v[190:193], v169 offset:1024
	ds_read_b128 v[194:197], v169 offset:2048
	ds_read_b128 v[198:201], v169 offset:3072
	ds_read_b128 v[202:205], v169 offset:4096
	ds_read_b128 v[206:209], v169 offset:5120
	ds_read_b128 v[210:213], v169 offset:6144
	ds_read_b128 v[214:217], v169 offset:7168
	global_load_lds_dwordx4 v[162:163], off
	v_lshl_add_u64 v[162:163], s[36:37], 0, v[156:157]
	s_add_i32 m0, s52, 0xe000
	s_nop 0
	global_load_lds_dwordx4 v[162:163], off
	s_setprio 1
	s_waitcnt vmcnt(8) lgkmcnt(0)
	s_barrier
	v_mfma_i32_16x16x64_i8 v[126:129], v[130:133], v[186:189], v[126:129]
	v_mfma_i32_16x16x64_i8 v[122:125], v[138:141], v[186:189], v[122:125]
	v_mfma_i32_16x16x64_i8 v[110:113], v[130:133], v[194:197], v[110:113]
	v_mfma_i32_16x16x64_i8 v[106:109], v[138:141], v[194:197], v[106:109]
	v_mfma_i32_16x16x64_i8 v[94:97], v[130:133], v[202:205], v[94:97]
	v_mfma_i32_16x16x64_i8 v[90:93], v[138:141], v[202:205], v[90:93]
	v_mfma_i32_16x16x64_i8 v[78:81], v[130:133], v[210:213], v[78:81]
	v_mfma_i32_16x16x64_i8 v[74:77], v[138:141], v[210:213], v[74:77]
	v_mfma_i32_16x16x64_i8 v[126:129], v[134:137], v[190:193], v[126:129]
	v_mfma_i32_16x16x64_i8 v[122:125], v[142:145], v[190:193], v[122:125]
	v_mfma_i32_16x16x64_i8 v[110:113], v[134:137], v[198:201], v[110:113]
	v_mfma_i32_16x16x64_i8 v[106:109], v[142:145], v[198:201], v[106:109]
	v_mfma_i32_16x16x64_i8 v[94:97], v[134:137], v[206:209], v[94:97]
	v_mfma_i32_16x16x64_i8 v[90:93], v[142:145], v[206:209], v[90:93]
	v_mfma_i32_16x16x64_i8 v[78:81], v[134:137], v[214:217], v[78:81]
	v_mfma_i32_16x16x64_i8 v[74:77], v[142:145], v[214:217], v[74:77]
	v_mfma_i32_16x16x64_i8 v[118:121], v[170:173], v[186:189], v[118:121]
	v_mfma_i32_16x16x64_i8 v[114:117], v[178:181], v[186:189], v[114:117]
	v_mfma_i32_16x16x64_i8 v[102:105], v[170:173], v[194:197], v[102:105]
	v_mfma_i32_16x16x64_i8 v[98:101], v[178:181], v[194:197], v[98:101]
	v_mfma_i32_16x16x64_i8 v[86:89], v[170:173], v[202:205], v[86:89]
	v_mfma_i32_16x16x64_i8 v[82:85], v[178:181], v[202:205], v[82:85]
	v_mfma_i32_16x16x64_i8 v[70:73], v[170:173], v[210:213], v[70:73]
	v_mfma_i32_16x16x64_i8 v[66:69], v[178:181], v[210:213], v[66:69]
	v_mfma_i32_16x16x64_i8 v[118:121], v[174:177], v[190:193], v[118:121]
	v_mfma_i32_16x16x64_i8 v[114:117], v[182:185], v[190:193], v[114:117]
	v_mfma_i32_16x16x64_i8 v[102:105], v[174:177], v[198:201], v[102:105]
	v_mfma_i32_16x16x64_i8 v[98:101], v[182:185], v[198:201], v[98:101]
	v_mfma_i32_16x16x64_i8 v[86:89], v[174:177], v[206:209], v[86:89]
	v_mfma_i32_16x16x64_i8 v[82:85], v[182:185], v[206:209], v[82:85]
	v_mfma_i32_16x16x64_i8 v[70:73], v[174:177], v[214:217], v[70:73]
	s_setprio 0
	v_mfma_i32_16x16x64_i8 v[66:69], v[182:185], v[214:217], v[66:69]
	s_barrier
	s_add_i32 s36, s61, s51
	v_lshl_add_u64 v[162:163], s[44:45], 0, v[150:151]
	s_mov_b32 m0, s36
	ds_read_b128 v[186:189], v169 offset:16384
	ds_read_b128 v[190:193], v169 offset:17408
	ds_read_b128 v[194:197], v169 offset:18432
	ds_read_b128 v[198:201], v169 offset:19456
	ds_read_b128 v[202:205], v169 offset:20480
	ds_read_b128 v[206:209], v169 offset:21504
	ds_read_b128 v[210:213], v169 offset:22528
	ds_read_b128 v[214:217], v169 offset:23552
	global_load_lds_dwordx4 v[162:163], off
	s_add_i32 m0, s36, 0x2000
	s_add_u32 s36, s44, 0x158000
	v_lshl_add_u64 v[218:219], s[44:45], 0, v[146:147]
	s_addc_u32 s37, s45, 0
	s_add_i32 s78, s62, s51
	global_load_lds_dwordx4 v[218:219], off
	v_lshl_add_u64 v[220:221], s[36:37], 0, v[150:151]
	s_mov_b32 m0, s78
	v_lshl_add_u64 v[222:223], s[46:47], 0, v[148:149]
	global_load_lds_dwordx4 v[220:221], off
	v_lshl_add_u64 v[220:221], s[36:37], 0, v[146:147]
	s_add_i32 m0, s78, 0x2000
	s_nop 0
	global_load_lds_dwordx4 v[220:221], off
	v_lshl_add_u64 v[220:221], s[46:47], 0, v[152:153]
	s_mov_b32 m0, s52
	s_nop 0
	global_load_lds_dwordx4 v[220:221], off
	s_mov_b32 m0, s53
	s_nop 0
	global_load_lds_dwordx4 v[222:223], off
	s_setprio 1
	s_waitcnt vmcnt(8) lgkmcnt(0)
	s_barrier
	v_mfma_i32_16x16x64_i8 v[62:65], v[130:133], v[186:189], v[62:65]
	v_mfma_i32_16x16x64_i8 v[58:61], v[138:141], v[186:189], v[58:61]
	v_mfma_i32_16x16x64_i8 v[46:49], v[130:133], v[194:197], v[46:49]
	v_mfma_i32_16x16x64_i8 v[42:45], v[138:141], v[194:197], v[42:45]
	v_mfma_i32_16x16x64_i8 v[30:33], v[130:133], v[202:205], v[30:33]
	v_mfma_i32_16x16x64_i8 v[26:29], v[138:141], v[202:205], v[26:29]
	v_mfma_i32_16x16x64_i8 v[14:17], v[130:133], v[210:213], v[14:17]
	v_mfma_i32_16x16x64_i8 v[10:13], v[138:141], v[210:213], v[10:13]
	v_mfma_i32_16x16x64_i8 v[62:65], v[134:137], v[190:193], v[62:65]
	v_mfma_i32_16x16x64_i8 v[58:61], v[142:145], v[190:193], v[58:61]
	v_mfma_i32_16x16x64_i8 v[46:49], v[134:137], v[198:201], v[46:49]
	v_mfma_i32_16x16x64_i8 v[42:45], v[142:145], v[198:201], v[42:45]
	v_mfma_i32_16x16x64_i8 v[30:33], v[134:137], v[206:209], v[30:33]
	v_mfma_i32_16x16x64_i8 v[26:29], v[142:145], v[206:209], v[26:29]
	v_mfma_i32_16x16x64_i8 v[14:17], v[134:137], v[214:217], v[14:17]
	v_mfma_i32_16x16x64_i8 v[10:13], v[142:145], v[214:217], v[10:13]
	v_mfma_i32_16x16x64_i8 v[54:57], v[170:173], v[186:189], v[54:57]
	v_mfma_i32_16x16x64_i8 v[50:53], v[178:181], v[186:189], v[50:53]
	v_mfma_i32_16x16x64_i8 v[38:41], v[170:173], v[194:197], v[38:41]
	v_mfma_i32_16x16x64_i8 v[34:37], v[178:181], v[194:197], v[34:37]
	v_mfma_i32_16x16x64_i8 v[22:25], v[170:173], v[202:205], v[22:25]
	v_mfma_i32_16x16x64_i8 v[18:21], v[178:181], v[202:205], v[18:21]
	v_mfma_i32_16x16x64_i8 v[6:9], v[170:173], v[210:213], v[6:9]
	v_mfma_i32_16x16x64_i8 v[2:5], v[178:181], v[210:213], v[2:5]
	v_mfma_i32_16x16x64_i8 v[54:57], v[174:177], v[190:193], v[54:57]
	v_mfma_i32_16x16x64_i8 v[50:53], v[182:185], v[190:193], v[50:53]
	v_mfma_i32_16x16x64_i8 v[38:41], v[174:177], v[198:201], v[38:41]
	v_mfma_i32_16x16x64_i8 v[34:37], v[182:185], v[198:201], v[34:37]
	v_mfma_i32_16x16x64_i8 v[22:25], v[174:177], v[206:209], v[22:25]
	v_mfma_i32_16x16x64_i8 v[18:21], v[182:185], v[206:209], v[18:21]
	v_mfma_i32_16x16x64_i8 v[6:9], v[174:177], v[214:217], v[6:9]
	s_setprio 0
	v_mfma_i32_16x16x64_i8 v[2:5], v[182:185], v[214:217], v[2:5]
	s_barrier
	s_add_i32 s78, 0, 0x18000
	s_add_i32 s79, 0, 0x1c000
	v_add_u32_e32 v142, s78, v166
	v_add_u32_e32 v182, s79, v166
	ds_read_b128 v[130:133], v142
	ds_read_b128 v[134:137], v142 offset:1024
	ds_read_b128 v[138:141], v142 offset:2048
	ds_read_b128 v[142:145], v142 offset:3072
	ds_read_b128 v[170:173], v182
	ds_read_b128 v[174:177], v182 offset:1024
	ds_read_b128 v[178:181], v182 offset:2048
	ds_read_b128 v[182:185], v182 offset:3072
	s_add_u32 s36, s46, 0x158000
	s_addc_u32 s37, s47, 0
	s_mov_b32 m0, s54
	v_lshl_add_u64 v[224:225], s[36:37], 0, v[152:153]
	ds_read_b128 v[186:189], v169 offset:32768
	ds_read_b128 v[190:193], v169 offset:33792
	ds_read_b128 v[194:197], v169 offset:34816
	ds_read_b128 v[198:201], v169 offset:35840
	ds_read_b128 v[202:205], v169 offset:36864
	ds_read_b128 v[206:209], v169 offset:37888
	ds_read_b128 v[210:213], v169 offset:38912
	ds_read_b128 v[214:217], v169 offset:39936
	global_load_lds_dwordx4 v[224:225], off
	v_lshl_add_u64 v[224:225], s[36:37], 0, v[148:149]
	s_mov_b32 m0, s55
	s_nop 0
	global_load_lds_dwordx4 v[224:225], off
	s_setprio 1
	s_waitcnt vmcnt(8) lgkmcnt(0)
	s_barrier
	v_mfma_i32_16x16x64_i8 v[126:129], v[130:133], v[186:189], v[126:129]
	v_mfma_i32_16x16x64_i8 v[122:125], v[138:141], v[186:189], v[122:125]
	v_mfma_i32_16x16x64_i8 v[110:113], v[130:133], v[194:197], v[110:113]
	v_mfma_i32_16x16x64_i8 v[106:109], v[138:141], v[194:197], v[106:109]
	v_mfma_i32_16x16x64_i8 v[94:97], v[130:133], v[202:205], v[94:97]
	v_mfma_i32_16x16x64_i8 v[90:93], v[138:141], v[202:205], v[90:93]
	v_mfma_i32_16x16x64_i8 v[78:81], v[130:133], v[210:213], v[78:81]
	v_mfma_i32_16x16x64_i8 v[74:77], v[138:141], v[210:213], v[74:77]
	v_mfma_i32_16x16x64_i8 v[126:129], v[134:137], v[190:193], v[126:129]
	v_mfma_i32_16x16x64_i8 v[122:125], v[142:145], v[190:193], v[122:125]
	v_mfma_i32_16x16x64_i8 v[110:113], v[134:137], v[198:201], v[110:113]
	v_mfma_i32_16x16x64_i8 v[106:109], v[142:145], v[198:201], v[106:109]
	v_mfma_i32_16x16x64_i8 v[94:97], v[134:137], v[206:209], v[94:97]
	v_mfma_i32_16x16x64_i8 v[90:93], v[142:145], v[206:209], v[90:93]
	v_mfma_i32_16x16x64_i8 v[78:81], v[134:137], v[214:217], v[78:81]
	v_mfma_i32_16x16x64_i8 v[74:77], v[142:145], v[214:217], v[74:77]
	v_mfma_i32_16x16x64_i8 v[118:121], v[170:173], v[186:189], v[118:121]
	v_mfma_i32_16x16x64_i8 v[114:117], v[178:181], v[186:189], v[114:117]
	v_mfma_i32_16x16x64_i8 v[102:105], v[170:173], v[194:197], v[102:105]
	v_mfma_i32_16x16x64_i8 v[98:101], v[178:181], v[194:197], v[98:101]
	v_mfma_i32_16x16x64_i8 v[86:89], v[170:173], v[202:205], v[86:89]
	v_mfma_i32_16x16x64_i8 v[82:85], v[178:181], v[202:205], v[82:85]
	v_mfma_i32_16x16x64_i8 v[70:73], v[170:173], v[210:213], v[70:73]
	v_mfma_i32_16x16x64_i8 v[66:69], v[178:181], v[210:213], v[66:69]
	v_mfma_i32_16x16x64_i8 v[118:121], v[174:177], v[190:193], v[118:121]
	v_mfma_i32_16x16x64_i8 v[114:117], v[182:185], v[190:193], v[114:117]
	v_mfma_i32_16x16x64_i8 v[102:105], v[174:177], v[198:201], v[102:105]
	v_mfma_i32_16x16x64_i8 v[98:101], v[182:185], v[198:201], v[98:101]
	v_mfma_i32_16x16x64_i8 v[86:89], v[174:177], v[206:209], v[86:89]
	v_mfma_i32_16x16x64_i8 v[82:85], v[182:185], v[206:209], v[82:85]
	v_mfma_i32_16x16x64_i8 v[70:73], v[174:177], v[214:217], v[70:73]
	s_setprio 0
	v_mfma_i32_16x16x64_i8 v[66:69], v[182:185], v[214:217], v[66:69]
	s_barrier
	s_add_i32 s36, s78, s51
	v_lshl_add_u64 v[162:163], v[162:163], 0, s[14:15]
	s_mov_b32 m0, s36
	ds_read_b128 v[186:189], v169 offset:49152
	ds_read_b128 v[190:193], v169 offset:50176
	ds_read_b128 v[194:197], v169 offset:51200
	ds_read_b128 v[198:201], v169 offset:52224
	ds_read_b128 v[202:205], v169 offset:53248
	ds_read_b128 v[206:209], v169 offset:54272
	ds_read_b128 v[210:213], v169 offset:55296
	ds_read_b128 v[214:217], v169 offset:56320
	global_load_lds_dwordx4 v[162:163], off
	s_add_i32 m0, s36, 0x2000
	s_add_u32 s36, s44, 0x158080
	v_lshl_add_u64 v[162:163], v[218:219], 0, s[14:15]
	s_addc_u32 s37, s45, 0
	s_add_i32 s44, s79, s51
	global_load_lds_dwordx4 v[162:163], off
	v_lshl_add_u64 v[162:163], s[36:37], 0, v[150:151]
	s_mov_b32 m0, s44
	s_nop 0
	global_load_lds_dwordx4 v[162:163], off
	v_lshl_add_u64 v[162:163], s[36:37], 0, v[146:147]
	s_add_i32 m0, s44, 0x2000
	s_nop 0
	global_load_lds_dwordx4 v[162:163], off
	v_lshl_add_u64 v[162:163], v[220:221], 0, s[14:15]
	s_mov_b32 m0, s59
	s_nop 0
	global_load_lds_dwordx4 v[162:163], off
	v_lshl_add_u64 v[162:163], v[222:223], 0, s[14:15]
	s_mov_b32 m0, s60
	s_nop 0
	global_load_lds_dwordx4 v[162:163], off
	s_setprio 1
	s_waitcnt vmcnt(8) lgkmcnt(0)
	s_barrier
	v_mfma_i32_16x16x64_i8 v[62:65], v[130:133], v[186:189], v[62:65]
	v_mfma_i32_16x16x64_i8 v[58:61], v[138:141], v[186:189], v[58:61]
	v_mfma_i32_16x16x64_i8 v[46:49], v[130:133], v[194:197], v[46:49]
	v_mfma_i32_16x16x64_i8 v[42:45], v[138:141], v[194:197], v[42:45]
	v_mfma_i32_16x16x64_i8 v[30:33], v[130:133], v[202:205], v[30:33]
	v_mfma_i32_16x16x64_i8 v[26:29], v[138:141], v[202:205], v[26:29]
	v_mfma_i32_16x16x64_i8 v[14:17], v[130:133], v[210:213], v[14:17]
	v_mfma_i32_16x16x64_i8 v[10:13], v[138:141], v[210:213], v[10:13]
	v_mfma_i32_16x16x64_i8 v[62:65], v[134:137], v[190:193], v[62:65]
	v_mfma_i32_16x16x64_i8 v[58:61], v[142:145], v[190:193], v[58:61]
	v_mfma_i32_16x16x64_i8 v[46:49], v[134:137], v[198:201], v[46:49]
	v_mfma_i32_16x16x64_i8 v[42:45], v[142:145], v[198:201], v[42:45]
	v_mfma_i32_16x16x64_i8 v[30:33], v[134:137], v[206:209], v[30:33]
	v_mfma_i32_16x16x64_i8 v[26:29], v[142:145], v[206:209], v[26:29]
	v_mfma_i32_16x16x64_i8 v[14:17], v[134:137], v[214:217], v[14:17]
	v_mfma_i32_16x16x64_i8 v[10:13], v[142:145], v[214:217], v[10:13]
	v_mfma_i32_16x16x64_i8 v[54:57], v[170:173], v[186:189], v[54:57]
	v_mfma_i32_16x16x64_i8 v[50:53], v[178:181], v[186:189], v[50:53]
	v_mfma_i32_16x16x64_i8 v[38:41], v[170:173], v[194:197], v[38:41]
	v_mfma_i32_16x16x64_i8 v[34:37], v[178:181], v[194:197], v[34:37]
	v_mfma_i32_16x16x64_i8 v[22:25], v[170:173], v[202:205], v[22:25]
	v_mfma_i32_16x16x64_i8 v[18:21], v[178:181], v[202:205], v[18:21]
	v_mfma_i32_16x16x64_i8 v[6:9], v[170:173], v[210:213], v[6:9]
	v_mfma_i32_16x16x64_i8 v[2:5], v[178:181], v[210:213], v[2:5]
	v_mfma_i32_16x16x64_i8 v[54:57], v[174:177], v[190:193], v[54:57]
	v_mfma_i32_16x16x64_i8 v[50:53], v[182:185], v[190:193], v[50:53]
	v_mfma_i32_16x16x64_i8 v[38:41], v[174:177], v[198:201], v[38:41]
	v_mfma_i32_16x16x64_i8 v[34:37], v[182:185], v[198:201], v[34:37]
	v_mfma_i32_16x16x64_i8 v[22:25], v[174:177], v[206:209], v[22:25]
	v_mfma_i32_16x16x64_i8 v[18:21], v[182:185], v[206:209], v[18:21]
	v_mfma_i32_16x16x64_i8 v[6:9], v[174:177], v[214:217], v[6:9]
	s_setprio 0
	v_mfma_i32_16x16x64_i8 v[2:5], v[182:185], v[214:217], v[2:5]
	s_barrier
	s_add_i32 s77, s77, 2
	s_add_u32 s75, s75, 0x100
	s_addc_u32 s76, s76, 0
	s_cmpk_gt_u32 s77, 0x53
	s_mov_b64 s[36:37], s[38:39]
	s_cbranch_scc0 .LBB0_1951
	s_and_b64 vcc, exec, s[16:17]
	s_cbranch_vccz .LBB0_1954
	s_barrier
